# hand-written MLA uq / ukv epilogues: row statistics loaded together, rstd applied in place, q_rope tables double-buffered, scalar row pointers
# speedup vs baseline: 1.0406x; 1.0061x over previous
.LBB0_639:
	s_and_b64 vcc, exec, s[4:5]
	s_cbranch_vccz .LBB0_686
	s_load_dwordx2 s[4:5], s[0:1], 0xd0
	v_readlane_b32 s48, v254, 36
	v_readlane_b32 s49, v254, 45
	v_readlane_b32 s50, v255, 29
	v_lshlrev_b32_e32 v131, 4, v189
	v_lshlrev_b32_e32 v130, 11, v189
	v_lshl_add_u32 v130, v191, 4, v130
	s_lshl_b32 s51, s48, 8
	s_add_u32 s51, s51, s49
	s_lshl_b32 s35, s51, 11
	s_and_b32 s36, s74, 3
	s_lshl_b32 s36, s36, 9
	s_add_u32 s35, s35, s36
	s_lshl_b32 s36, s50, 1
	s_add_u32 s35, s35, s36
	s_mov_b32 s36, 0x7800000
	s_cmp_lt_u32 s74, 4
	s_cselect_b32 s36, s36, 0x9400000
	s_add_u32 s35, s35, s36
	s_mov_b32 s33, 0x8000
	s_mov_b32 s34, 0x28000
	s_waitcnt lgkmcnt(0)
	s_add_u32 s6, s4, s35
	s_addc_u32 s7, s5, 0
	s_mov_b32 s36, s51
	s_cmp_lt_u32 s48, 32
	s_cbranch_scc1 .Lk2_stats
	s_sub_u32 s36, s48, 32
	s_mul_hi_u32 s37, s36, 0xaaaaaaab
	s_lshr_b32 s37, s37, 2
	s_mul_i32 s58, s37, 6
	s_sub_u32 s58, s36, s58
	s_cmp_lt_u32 s58, 2
	s_cbranch_scc1 .Lk2_cache
	s_lshl_b32 s36, s37, 10
	s_sub_u32 s58, s58, 2
	s_lshl_b32 s58, s58, 8
	s_add_u32 s36, s36, s58
	s_add_u32 s36, s36, s49
	s_add_u32 s36, s36, 0x2000
.Lk2_stats:
	s_lshl_b32 s36, s36, 4
	s_add_u32 s36, s36, 0x200000
	s_add_u32 s24, s4, s36
	s_addc_u32 s25, s5, 0
	global_load_dwordx4 v[154:157], v131, s[24:25] offset:0
	global_load_dwordx4 v[158:161], v131, s[24:25] offset:256
	global_load_dwordx4 v[162:165], v131, s[24:25] offset:512
	global_load_dwordx4 v[166:169], v131, s[24:25] offset:768
	global_load_dwordx4 v[170:173], v131, s[24:25] offset:2048
	global_load_dwordx4 v[174:177], v131, s[24:25] offset:2304
	global_load_dwordx4 v[178:181], v131, s[24:25] offset:2560
	global_load_dwordx4 v[202:205], v131, s[24:25] offset:2816
	s_waitcnt vmcnt(0)
	v_add_f32_e32 v142, v155, v154
	v_add_f32_e32 v143, v156, v157
	v_add_f32_e32 v142, v142, v143
	v_fmamk_f32 v134, v142, 0x3b800000, v242
	v_add_f32_e32 v142, v159, v158
	v_add_f32_e32 v143, v160, v161
	v_add_f32_e32 v142, v142, v143
	v_fmamk_f32 v135, v142, 0x3b800000, v242
	v_add_f32_e32 v142, v163, v162
	v_add_f32_e32 v143, v164, v165
	v_add_f32_e32 v142, v142, v143
	v_fmamk_f32 v136, v142, 0x3b800000, v242
	v_add_f32_e32 v142, v167, v166
	v_add_f32_e32 v143, v168, v169
	v_add_f32_e32 v142, v142, v143
	v_fmamk_f32 v137, v142, 0x3b800000, v242
	v_add_f32_e32 v142, v171, v170
	v_add_f32_e32 v143, v172, v173
	v_add_f32_e32 v142, v142, v143
	v_fmamk_f32 v138, v142, 0x3b800000, v242
	v_add_f32_e32 v142, v175, v174
	v_add_f32_e32 v143, v176, v177
	v_add_f32_e32 v142, v142, v143
	v_fmamk_f32 v139, v142, 0x3b800000, v242
	v_add_f32_e32 v142, v179, v178
	v_add_f32_e32 v143, v180, v181
	v_add_f32_e32 v142, v142, v143
	v_fmamk_f32 v140, v142, 0x3b800000, v242
	v_add_f32_e32 v142, v203, v202
	v_add_f32_e32 v143, v204, v205
	v_add_f32_e32 v142, v142, v143
	v_fmamk_f32 v141, v142, 0x3b800000, v242
	v_rsq_f32_e32 v134, v134
	v_rsq_f32_e32 v135, v135
	v_rsq_f32_e32 v136, v136
	v_rsq_f32_e32 v137, v137
	v_rsq_f32_e32 v138, v138
	v_rsq_f32_e32 v139, v139
	v_rsq_f32_e32 v140, v140
	v_rsq_f32_e32 v141, v141
	s_branch .Lk2_body
.Lk2_cache:
	v_mov_b32_e32 v134, 1.0
	v_mov_b32_e32 v135, 1.0
	v_mov_b32_e32 v136, 1.0
	v_mov_b32_e32 v137, 1.0
	v_mov_b32_e32 v138, 1.0
	v_mov_b32_e32 v139, 1.0
	v_mov_b32_e32 v140, 1.0
	v_mov_b32_e32 v141, 1.0
.Lk2_body:
	s_nop 0
	v_pk_mul_f32 v[126:127], v[126:127], v[134:135] op_sel_hi:[1,0]
	v_pk_mul_f32 v[128:129], v[128:129], v[134:135] op_sel_hi:[1,0]
	v_pk_mul_f32 v[122:123], v[122:123], v[134:135] op_sel_hi:[1,0]
	v_pk_mul_f32 v[124:125], v[124:125], v[134:135] op_sel_hi:[1,0]
	v_pk_mul_f32 v[118:119], v[118:119], v[134:135] op_sel_hi:[1,0]
	v_pk_mul_f32 v[120:121], v[120:121], v[134:135] op_sel_hi:[1,0]
	v_pk_mul_f32 v[114:115], v[114:115], v[134:135] op_sel_hi:[1,0]
	v_pk_mul_f32 v[116:117], v[116:117], v[134:135] op_sel_hi:[1,0]
	v_cvt_pk_bf16_f32 v146, v126, v127
	v_cvt_pk_bf16_f32 v147, v128, v129
	v_cvt_pk_bf16_f32 v148, v122, v123
	v_cvt_pk_bf16_f32 v149, v124, v125
	global_store_dwordx4 v130, v[146:149], s[6:7]
	v_cvt_pk_bf16_f32 v150, v118, v119
	v_cvt_pk_bf16_f32 v151, v120, v121
	v_cvt_pk_bf16_f32 v152, v114, v115
	v_cvt_pk_bf16_f32 v153, v116, v117
	global_store_dwordx4 v130, v[150:153], s[6:7] offset:256
	s_add_u32 s6, s6, s33
	s_addc_u32 s7, s7, 0
	v_pk_mul_f32 v[108:109], v[108:109], v[134:135] op_sel:[0,1] op_sel_hi:[1,1]
	v_pk_mul_f32 v[110:111], v[110:111], v[134:135] op_sel:[0,1] op_sel_hi:[1,1]
	v_pk_mul_f32 v[104:105], v[104:105], v[134:135] op_sel:[0,1] op_sel_hi:[1,1]
	v_pk_mul_f32 v[106:107], v[106:107], v[134:135] op_sel:[0,1] op_sel_hi:[1,1]
	v_pk_mul_f32 v[100:101], v[100:101], v[134:135] op_sel:[0,1] op_sel_hi:[1,1]
	v_pk_mul_f32 v[102:103], v[102:103], v[134:135] op_sel:[0,1] op_sel_hi:[1,1]
	v_pk_mul_f32 v[96:97], v[96:97], v[134:135] op_sel:[0,1] op_sel_hi:[1,1]
	v_pk_mul_f32 v[98:99], v[98:99], v[134:135] op_sel:[0,1] op_sel_hi:[1,1]
	v_cvt_pk_bf16_f32 v146, v108, v109
	v_cvt_pk_bf16_f32 v147, v110, v111
	v_cvt_pk_bf16_f32 v148, v104, v105
	v_cvt_pk_bf16_f32 v149, v106, v107
	global_store_dwordx4 v130, v[146:149], s[6:7]
	v_cvt_pk_bf16_f32 v150, v100, v101
	v_cvt_pk_bf16_f32 v151, v102, v103
	v_cvt_pk_bf16_f32 v152, v96, v97
	v_cvt_pk_bf16_f32 v153, v98, v99
	global_store_dwordx4 v130, v[150:153], s[6:7] offset:256
	s_add_u32 s6, s6, s33
	s_addc_u32 s7, s7, 0
	v_pk_mul_f32 v[92:93], v[92:93], v[136:137] op_sel_hi:[1,0]
	v_pk_mul_f32 v[94:95], v[94:95], v[136:137] op_sel_hi:[1,0]
	v_pk_mul_f32 v[88:89], v[88:89], v[136:137] op_sel_hi:[1,0]
	v_pk_mul_f32 v[90:91], v[90:91], v[136:137] op_sel_hi:[1,0]
	v_pk_mul_f32 v[84:85], v[84:85], v[136:137] op_sel_hi:[1,0]
	v_pk_mul_f32 v[86:87], v[86:87], v[136:137] op_sel_hi:[1,0]
	v_pk_mul_f32 v[80:81], v[80:81], v[136:137] op_sel_hi:[1,0]
	v_pk_mul_f32 v[82:83], v[82:83], v[136:137] op_sel_hi:[1,0]
	v_cvt_pk_bf16_f32 v146, v92, v93
	v_cvt_pk_bf16_f32 v147, v94, v95
	v_cvt_pk_bf16_f32 v148, v88, v89
	v_cvt_pk_bf16_f32 v149, v90, v91
	global_store_dwordx4 v130, v[146:149], s[6:7]
	v_cvt_pk_bf16_f32 v150, v84, v85
	v_cvt_pk_bf16_f32 v151, v86, v87
	v_cvt_pk_bf16_f32 v152, v80, v81
	v_cvt_pk_bf16_f32 v153, v82, v83
	global_store_dwordx4 v130, v[150:153], s[6:7] offset:256
	s_add_u32 s6, s6, s33
	s_addc_u32 s7, s7, 0
	v_pk_mul_f32 v[76:77], v[76:77], v[136:137] op_sel:[0,1] op_sel_hi:[1,1]
	v_pk_mul_f32 v[78:79], v[78:79], v[136:137] op_sel:[0,1] op_sel_hi:[1,1]
	v_pk_mul_f32 v[72:73], v[72:73], v[136:137] op_sel:[0,1] op_sel_hi:[1,1]
	v_pk_mul_f32 v[74:75], v[74:75], v[136:137] op_sel:[0,1] op_sel_hi:[1,1]
	v_pk_mul_f32 v[68:69], v[68:69], v[136:137] op_sel:[0,1] op_sel_hi:[1,1]
	v_pk_mul_f32 v[70:71], v[70:71], v[136:137] op_sel:[0,1] op_sel_hi:[1,1]
	v_pk_mul_f32 v[64:65], v[64:65], v[136:137] op_sel:[0,1] op_sel_hi:[1,1]
	v_pk_mul_f32 v[66:67], v[66:67], v[136:137] op_sel:[0,1] op_sel_hi:[1,1]
	v_cvt_pk_bf16_f32 v146, v76, v77
	v_cvt_pk_bf16_f32 v147, v78, v79
	v_cvt_pk_bf16_f32 v148, v72, v73
	v_cvt_pk_bf16_f32 v149, v74, v75
	global_store_dwordx4 v130, v[146:149], s[6:7]
	v_cvt_pk_bf16_f32 v150, v68, v69
	v_cvt_pk_bf16_f32 v151, v70, v71
	v_cvt_pk_bf16_f32 v152, v64, v65
	v_cvt_pk_bf16_f32 v153, v66, v67
	global_store_dwordx4 v130, v[150:153], s[6:7] offset:256
	s_add_u32 s6, s6, s34
	s_addc_u32 s7, s7, 0
	v_pk_mul_f32 v[60:61], v[60:61], v[138:139] op_sel_hi:[1,0]
	v_pk_mul_f32 v[62:63], v[62:63], v[138:139] op_sel_hi:[1,0]
	v_pk_mul_f32 v[56:57], v[56:57], v[138:139] op_sel_hi:[1,0]
	v_pk_mul_f32 v[58:59], v[58:59], v[138:139] op_sel_hi:[1,0]
	v_pk_mul_f32 v[52:53], v[52:53], v[138:139] op_sel_hi:[1,0]
	v_pk_mul_f32 v[54:55], v[54:55], v[138:139] op_sel_hi:[1,0]
	v_pk_mul_f32 v[48:49], v[48:49], v[138:139] op_sel_hi:[1,0]
	v_pk_mul_f32 v[50:51], v[50:51], v[138:139] op_sel_hi:[1,0]
	v_cvt_pk_bf16_f32 v146, v60, v61
	v_cvt_pk_bf16_f32 v147, v62, v63
	v_cvt_pk_bf16_f32 v148, v56, v57
	v_cvt_pk_bf16_f32 v149, v58, v59
	global_store_dwordx4 v130, v[146:149], s[6:7]
	v_cvt_pk_bf16_f32 v150, v52, v53
	v_cvt_pk_bf16_f32 v151, v54, v55
	v_cvt_pk_bf16_f32 v152, v48, v49
	v_cvt_pk_bf16_f32 v153, v50, v51
	global_store_dwordx4 v130, v[150:153], s[6:7] offset:256
	s_add_u32 s6, s6, s33
	s_addc_u32 s7, s7, 0
	v_pk_mul_f32 v[44:45], v[44:45], v[138:139] op_sel:[0,1] op_sel_hi:[1,1]
	v_pk_mul_f32 v[46:47], v[46:47], v[138:139] op_sel:[0,1] op_sel_hi:[1,1]
	v_pk_mul_f32 v[40:41], v[40:41], v[138:139] op_sel:[0,1] op_sel_hi:[1,1]
	v_pk_mul_f32 v[42:43], v[42:43], v[138:139] op_sel:[0,1] op_sel_hi:[1,1]
	v_pk_mul_f32 v[36:37], v[36:37], v[138:139] op_sel:[0,1] op_sel_hi:[1,1]
	v_pk_mul_f32 v[38:39], v[38:39], v[138:139] op_sel:[0,1] op_sel_hi:[1,1]
	v_pk_mul_f32 v[32:33], v[32:33], v[138:139] op_sel:[0,1] op_sel_hi:[1,1]
	v_pk_mul_f32 v[34:35], v[34:35], v[138:139] op_sel:[0,1] op_sel_hi:[1,1]
	v_cvt_pk_bf16_f32 v146, v44, v45
	v_cvt_pk_bf16_f32 v147, v46, v47
	v_cvt_pk_bf16_f32 v148, v40, v41
	v_cvt_pk_bf16_f32 v149, v42, v43
	global_store_dwordx4 v130, v[146:149], s[6:7]
	v_cvt_pk_bf16_f32 v150, v36, v37
	v_cvt_pk_bf16_f32 v151, v38, v39
	v_cvt_pk_bf16_f32 v152, v32, v33
	v_cvt_pk_bf16_f32 v153, v34, v35
	global_store_dwordx4 v130, v[150:153], s[6:7] offset:256
	s_add_u32 s6, s6, s33
	s_addc_u32 s7, s7, 0
	v_pk_mul_f32 v[28:29], v[28:29], v[140:141] op_sel_hi:[1,0]
	v_pk_mul_f32 v[30:31], v[30:31], v[140:141] op_sel_hi:[1,0]
	v_pk_mul_f32 v[24:25], v[24:25], v[140:141] op_sel_hi:[1,0]
	v_pk_mul_f32 v[26:27], v[26:27], v[140:141] op_sel_hi:[1,0]
	v_pk_mul_f32 v[20:21], v[20:21], v[140:141] op_sel_hi:[1,0]
	v_pk_mul_f32 v[22:23], v[22:23], v[140:141] op_sel_hi:[1,0]
	v_pk_mul_f32 v[16:17], v[16:17], v[140:141] op_sel_hi:[1,0]
	v_pk_mul_f32 v[18:19], v[18:19], v[140:141] op_sel_hi:[1,0]
	v_cvt_pk_bf16_f32 v146, v28, v29
	v_cvt_pk_bf16_f32 v147, v30, v31
	v_cvt_pk_bf16_f32 v148, v24, v25
	v_cvt_pk_bf16_f32 v149, v26, v27
	global_store_dwordx4 v130, v[146:149], s[6:7]
	v_cvt_pk_bf16_f32 v150, v20, v21
	v_cvt_pk_bf16_f32 v151, v22, v23
	v_cvt_pk_bf16_f32 v152, v16, v17
	v_cvt_pk_bf16_f32 v153, v18, v19
	global_store_dwordx4 v130, v[150:153], s[6:7] offset:256
	s_add_u32 s6, s6, s33
	s_addc_u32 s7, s7, 0
	v_pk_mul_f32 v[12:13], v[12:13], v[140:141] op_sel:[0,1] op_sel_hi:[1,1]
	v_pk_mul_f32 v[14:15], v[14:15], v[140:141] op_sel:[0,1] op_sel_hi:[1,1]
	v_pk_mul_f32 v[4:5], v[4:5], v[140:141] op_sel:[0,1] op_sel_hi:[1,1]
	v_pk_mul_f32 v[6:7], v[6:7], v[140:141] op_sel:[0,1] op_sel_hi:[1,1]
	v_pk_mul_f32 v[8:9], v[8:9], v[140:141] op_sel:[0,1] op_sel_hi:[1,1]
	v_pk_mul_f32 v[10:11], v[10:11], v[140:141] op_sel:[0,1] op_sel_hi:[1,1]
	v_pk_mul_f32 v[0:1], v[0:1], v[140:141] op_sel:[0,1] op_sel_hi:[1,1]
	v_pk_mul_f32 v[2:3], v[2:3], v[140:141] op_sel:[0,1] op_sel_hi:[1,1]
	v_cvt_pk_bf16_f32 v146, v12, v13
	v_cvt_pk_bf16_f32 v147, v14, v15
	v_cvt_pk_bf16_f32 v148, v4, v5
	v_cvt_pk_bf16_f32 v149, v6, v7
	global_store_dwordx4 v130, v[146:149], s[6:7]
	v_cvt_pk_bf16_f32 v150, v8, v9
	v_cvt_pk_bf16_f32 v151, v10, v11
	v_cvt_pk_bf16_f32 v152, v0, v1
	v_cvt_pk_bf16_f32 v153, v2, v3
	global_store_dwordx4 v130, v[150:153], s[6:7] offset:256
	s_branch .LBB0_686

.Lm0_P2c:
	global_load_dwordx4 v[164:167], v132, s[8:9]
	global_load_dwordx4 v[168:171], v133, s[8:9]
	v_cmp_eq_u32_e64 s[50:51], 1, v191
	v_cmp_eq_u32_e64 s[58:59], 2, v191
	v_cmp_eq_u32_e64 s[96:97], 3, v191
	v_mul_f32_e32 v136, v127, v127
	v_fmac_f32_e32 v136, v126, v126
	v_fmac_f32_e32 v136, v128, v128
	v_mul_f32_e32 v160, v129, v129
	v_mul_f32_e32 v161, v123, v123
	v_add_f32_e32 v136, v160, v136
	v_fmac_f32_e32 v136, v122, v122
	v_mul_f32_e32 v160, v125, v125
	v_add_f32_e32 v136, v161, v136
	v_fmac_f32_e32 v136, v124, v124
	v_add_f32_e32 v136, v160, v136
	v_mul_f32_e32 v137, v109, v109
	v_fmac_f32_e32 v137, v108, v108
	v_fmac_f32_e32 v137, v110, v110
	v_mul_f32_e32 v160, v111, v111
	v_mul_f32_e32 v161, v105, v105
	v_add_f32_e32 v137, v160, v137
	v_fmac_f32_e32 v137, v104, v104
	v_mul_f32_e32 v160, v107, v107
	v_add_f32_e32 v137, v161, v137
	v_fmac_f32_e32 v137, v106, v106
	v_add_f32_e32 v137, v160, v137
	v_mul_f32_e32 v138, v93, v93
	v_fmac_f32_e32 v138, v92, v92
	v_fmac_f32_e32 v138, v94, v94
	v_mul_f32_e32 v160, v95, v95
	v_mul_f32_e32 v161, v89, v89
	v_add_f32_e32 v138, v160, v138
	v_fmac_f32_e32 v138, v88, v88
	v_mul_f32_e32 v160, v91, v91
	v_add_f32_e32 v138, v161, v138
	v_fmac_f32_e32 v138, v90, v90
	v_add_f32_e32 v138, v160, v138
	v_mul_f32_e32 v139, v77, v77
	v_fmac_f32_e32 v139, v76, v76
	v_fmac_f32_e32 v139, v78, v78
	v_mul_f32_e32 v160, v79, v79
	v_mul_f32_e32 v161, v73, v73
	v_add_f32_e32 v139, v160, v139
	v_fmac_f32_e32 v139, v72, v72
	v_mul_f32_e32 v160, v75, v75
	v_add_f32_e32 v139, v161, v139
	v_fmac_f32_e32 v139, v74, v74
	v_add_f32_e32 v139, v160, v139
	v_mul_f32_e32 v140, v61, v61
	v_fmac_f32_e32 v140, v60, v60
	v_fmac_f32_e32 v140, v62, v62
	v_mul_f32_e32 v160, v63, v63
	v_mul_f32_e32 v161, v57, v57
	v_add_f32_e32 v140, v160, v140
	v_fmac_f32_e32 v140, v56, v56
	v_mul_f32_e32 v160, v59, v59
	v_add_f32_e32 v140, v161, v140
	v_fmac_f32_e32 v140, v58, v58
	v_add_f32_e32 v140, v160, v140
	v_mul_f32_e32 v141, v45, v45
	v_fmac_f32_e32 v141, v44, v44
	v_fmac_f32_e32 v141, v46, v46
	v_mul_f32_e32 v160, v47, v47
	v_mul_f32_e32 v161, v41, v41
	v_add_f32_e32 v141, v160, v141
	v_fmac_f32_e32 v141, v40, v40
	v_mul_f32_e32 v160, v43, v43
	v_add_f32_e32 v141, v161, v141
	v_fmac_f32_e32 v141, v42, v42
	v_add_f32_e32 v141, v160, v141
	v_mul_f32_e32 v142, v29, v29
	v_fmac_f32_e32 v142, v28, v28
	v_fmac_f32_e32 v142, v30, v30
	v_mul_f32_e32 v160, v31, v31
	v_mul_f32_e32 v161, v25, v25
	v_add_f32_e32 v142, v160, v142
	v_fmac_f32_e32 v142, v24, v24
	v_mul_f32_e32 v160, v27, v27
	v_add_f32_e32 v142, v161, v142
	v_fmac_f32_e32 v142, v26, v26
	v_add_f32_e32 v142, v160, v142
	v_mul_f32_e32 v143, v13, v13
	v_fmac_f32_e32 v143, v12, v12
	v_fmac_f32_e32 v143, v14, v14
	v_mul_f32_e32 v160, v15, v15
	v_mul_f32_e32 v161, v5, v5
	v_add_f32_e32 v143, v160, v143
	v_fmac_f32_e32 v143, v4, v4
	v_mul_f32_e32 v160, v7, v7
	v_add_f32_e32 v143, v161, v143
	v_fmac_f32_e32 v143, v6, v6
	v_add_f32_e32 v143, v160, v143
	ds_swizzle_b32 v144, v136 offset:swizzle(SWAP,16)
	ds_swizzle_b32 v145, v137 offset:swizzle(SWAP,16)
	ds_swizzle_b32 v146, v138 offset:swizzle(SWAP,16)
	ds_swizzle_b32 v147, v139 offset:swizzle(SWAP,16)
	ds_swizzle_b32 v148, v140 offset:swizzle(SWAP,16)
	ds_swizzle_b32 v149, v141 offset:swizzle(SWAP,16)
	ds_swizzle_b32 v150, v142 offset:swizzle(SWAP,16)
	ds_swizzle_b32 v151, v143 offset:swizzle(SWAP,16)
	s_waitcnt lgkmcnt(0)
	v_add_f32_e32 v136, v136, v144
	v_add_f32_e32 v137, v137, v145
	v_add_f32_e32 v138, v138, v146
	v_add_f32_e32 v139, v139, v147
	v_add_f32_e32 v140, v140, v148
	v_add_f32_e32 v141, v141, v149
	v_add_f32_e32 v142, v142, v150
	v_add_f32_e32 v143, v143, v151
	v_mov_b32_e32 v144, v136
	v_mov_b32_e32 v145, v137
	v_mov_b32_e32 v146, v138
	v_mov_b32_e32 v147, v139
	v_mov_b32_e32 v148, v140
	v_mov_b32_e32 v149, v141
	v_mov_b32_e32 v150, v142
	v_mov_b32_e32 v151, v143
	s_nop 1
	v_permlane32_swap_b32 v136, v144
	v_permlane32_swap_b32 v137, v145
	v_permlane32_swap_b32 v138, v146
	v_permlane32_swap_b32 v139, v147
	v_permlane32_swap_b32 v140, v148
	v_permlane32_swap_b32 v141, v149
	v_permlane32_swap_b32 v142, v150
	v_permlane32_swap_b32 v143, v151
	s_nop 1
	v_add_f32_e32 v136, v136, v144
	v_add_f32_e32 v137, v137, v145
	v_add_f32_e32 v138, v138, v146
	v_add_f32_e32 v139, v139, v147
	v_add_f32_e32 v140, v140, v148
	v_add_f32_e32 v141, v141, v149
	v_add_f32_e32 v142, v142, v150
	v_add_f32_e32 v143, v143, v151
	s_add_u32 s8, s8, 0x400
	s_addc_u32 s9, s9, 0
	global_load_dwordx4 v[172:175], v132, s[8:9]
	global_load_dwordx4 v[176:179], v133, s[8:9]
	v_cvt_pk_bf16_f32 v152, v126, v127
	v_cvt_pk_bf16_f32 v153, v128, v129
	v_cvt_pk_bf16_f32 v154, v122, v123
	v_cvt_pk_bf16_f32 v155, v124, v125
	global_store_dwordx4 v130, v[152:155], s[6:7] sc1
	s_add_u32 s6, s6, s33
	s_addc_u32 s7, s7, 0
	s_waitcnt vmcnt(3)
	v_pk_mul_f32 v[162:163], v[118:119], v[168:169] op_sel:[1,0] op_sel_hi:[0,0]
	v_pk_fma_f32 v[118:119], v[118:119], v[164:165], v[162:163] op_sel:[0,0,0] op_sel_hi:[1,0,1] neg_lo:[0,0,1]
	v_pk_mul_f32 v[162:163], v[120:121], v[168:169] op_sel:[1,1] op_sel_hi:[0,1]
	v_pk_fma_f32 v[120:121], v[120:121], v[164:165], v[162:163] op_sel:[0,1,0] op_sel_hi:[1,1,1] neg_lo:[0,0,1]
	v_pk_mul_f32 v[162:163], v[114:115], v[170:171] op_sel:[1,0] op_sel_hi:[0,0]
	v_pk_fma_f32 v[114:115], v[114:115], v[166:167], v[162:163] op_sel:[0,0,0] op_sel_hi:[1,0,1] neg_lo:[0,0,1]
	v_pk_mul_f32 v[162:163], v[116:117], v[170:171] op_sel:[1,1] op_sel_hi:[0,1]
	v_pk_fma_f32 v[116:117], v[116:117], v[166:167], v[162:163] op_sel:[0,1,0] op_sel_hi:[1,1,1] neg_lo:[0,0,1]
	v_cvt_pk_bf16_f32 v156, v118, v119
	v_cvt_pk_bf16_f32 v157, v120, v121
	v_cvt_pk_bf16_f32 v158, v114, v115
	v_cvt_pk_bf16_f32 v159, v116, v117
	global_store_dwordx4 v131, v[156:159], s[48:49]
	s_add_u32 s48, s48, 0x400
	s_addc_u32 s49, s49, 0
	s_add_u32 s8, s8, 0x400
	s_addc_u32 s9, s9, 0
	global_load_dwordx4 v[164:167], v132, s[8:9]
	global_load_dwordx4 v[168:171], v133, s[8:9]
	v_cvt_pk_bf16_f32 v152, v108, v109
	v_cvt_pk_bf16_f32 v153, v110, v111
	v_cvt_pk_bf16_f32 v154, v104, v105
	v_cvt_pk_bf16_f32 v155, v106, v107
	global_store_dwordx4 v130, v[152:155], s[6:7] sc1
	s_add_u32 s6, s6, s33
	s_addc_u32 s7, s7, 0
	s_waitcnt vmcnt(5)
	v_pk_mul_f32 v[162:163], v[100:101], v[176:177] op_sel:[1,0] op_sel_hi:[0,0]
	v_pk_fma_f32 v[100:101], v[100:101], v[172:173], v[162:163] op_sel:[0,0,0] op_sel_hi:[1,0,1] neg_lo:[0,0,1]
	v_pk_mul_f32 v[162:163], v[102:103], v[176:177] op_sel:[1,1] op_sel_hi:[0,1]
	v_pk_fma_f32 v[102:103], v[102:103], v[172:173], v[162:163] op_sel:[0,1,0] op_sel_hi:[1,1,1] neg_lo:[0,0,1]
	v_pk_mul_f32 v[162:163], v[96:97], v[178:179] op_sel:[1,0] op_sel_hi:[0,0]
	v_pk_fma_f32 v[96:97], v[96:97], v[174:175], v[162:163] op_sel:[0,0,0] op_sel_hi:[1,0,1] neg_lo:[0,0,1]
	v_pk_mul_f32 v[162:163], v[98:99], v[178:179] op_sel:[1,1] op_sel_hi:[0,1]
	v_pk_fma_f32 v[98:99], v[98:99], v[174:175], v[162:163] op_sel:[0,1,0] op_sel_hi:[1,1,1] neg_lo:[0,0,1]
	v_cvt_pk_bf16_f32 v156, v100, v101
	v_cvt_pk_bf16_f32 v157, v102, v103
	v_cvt_pk_bf16_f32 v158, v96, v97
	v_cvt_pk_bf16_f32 v159, v98, v99
	global_store_dwordx4 v131, v[156:159], s[48:49]
	s_add_u32 s48, s48, 0x400
	s_addc_u32 s49, s49, 0
	s_add_u32 s8, s8, 0x400
	s_addc_u32 s9, s9, 0
	global_load_dwordx4 v[172:175], v132, s[8:9]
	global_load_dwordx4 v[176:179], v133, s[8:9]
	v_cvt_pk_bf16_f32 v152, v92, v93
	v_cvt_pk_bf16_f32 v153, v94, v95
	v_cvt_pk_bf16_f32 v154, v88, v89
	v_cvt_pk_bf16_f32 v155, v90, v91
	global_store_dwordx4 v130, v[152:155], s[6:7] sc1
	s_add_u32 s6, s6, s33
	s_addc_u32 s7, s7, 0
	s_waitcnt vmcnt(5)
	v_pk_mul_f32 v[162:163], v[84:85], v[168:169] op_sel:[1,0] op_sel_hi:[0,0]
	v_pk_fma_f32 v[84:85], v[84:85], v[164:165], v[162:163] op_sel:[0,0,0] op_sel_hi:[1,0,1] neg_lo:[0,0,1]
	v_pk_mul_f32 v[162:163], v[86:87], v[168:169] op_sel:[1,1] op_sel_hi:[0,1]
	v_pk_fma_f32 v[86:87], v[86:87], v[164:165], v[162:163] op_sel:[0,1,0] op_sel_hi:[1,1,1] neg_lo:[0,0,1]
	v_pk_mul_f32 v[162:163], v[80:81], v[170:171] op_sel:[1,0] op_sel_hi:[0,0]
	v_pk_fma_f32 v[80:81], v[80:81], v[166:167], v[162:163] op_sel:[0,0,0] op_sel_hi:[1,0,1] neg_lo:[0,0,1]
	v_pk_mul_f32 v[162:163], v[82:83], v[170:171] op_sel:[1,1] op_sel_hi:[0,1]
	v_pk_fma_f32 v[82:83], v[82:83], v[166:167], v[162:163] op_sel:[0,1,0] op_sel_hi:[1,1,1] neg_lo:[0,0,1]
	v_cvt_pk_bf16_f32 v156, v84, v85
	v_cvt_pk_bf16_f32 v157, v86, v87
	v_cvt_pk_bf16_f32 v158, v80, v81
	v_cvt_pk_bf16_f32 v159, v82, v83
	global_store_dwordx4 v131, v[156:159], s[48:49]
	s_add_u32 s48, s48, 0x400
	s_addc_u32 s49, s49, 0
	s_add_u32 s8, s8, 0x1400
	s_addc_u32 s9, s9, 0
	global_load_dwordx4 v[164:167], v132, s[8:9]
	global_load_dwordx4 v[168:171], v133, s[8:9]
	v_cvt_pk_bf16_f32 v152, v76, v77
	v_cvt_pk_bf16_f32 v153, v78, v79
	v_cvt_pk_bf16_f32 v154, v72, v73
	v_cvt_pk_bf16_f32 v155, v74, v75
	global_store_dwordx4 v130, v[152:155], s[6:7] sc1
	s_add_u32 s6, s6, s34
	s_addc_u32 s7, s7, 0
	s_waitcnt vmcnt(5)
	v_pk_mul_f32 v[162:163], v[68:69], v[176:177] op_sel:[1,0] op_sel_hi:[0,0]
	v_pk_fma_f32 v[68:69], v[68:69], v[172:173], v[162:163] op_sel:[0,0,0] op_sel_hi:[1,0,1] neg_lo:[0,0,1]
	v_pk_mul_f32 v[162:163], v[70:71], v[176:177] op_sel:[1,1] op_sel_hi:[0,1]
	v_pk_fma_f32 v[70:71], v[70:71], v[172:173], v[162:163] op_sel:[0,1,0] op_sel_hi:[1,1,1] neg_lo:[0,0,1]
	v_pk_mul_f32 v[162:163], v[64:65], v[178:179] op_sel:[1,0] op_sel_hi:[0,0]
	v_pk_fma_f32 v[64:65], v[64:65], v[174:175], v[162:163] op_sel:[0,0,0] op_sel_hi:[1,0,1] neg_lo:[0,0,1]
	v_pk_mul_f32 v[162:163], v[66:67], v[178:179] op_sel:[1,1] op_sel_hi:[0,1]
	v_pk_fma_f32 v[66:67], v[66:67], v[174:175], v[162:163] op_sel:[0,1,0] op_sel_hi:[1,1,1] neg_lo:[0,0,1]
	v_cvt_pk_bf16_f32 v156, v68, v69
	v_cvt_pk_bf16_f32 v157, v70, v71
	v_cvt_pk_bf16_f32 v158, v64, v65
	v_cvt_pk_bf16_f32 v159, v66, v67
	global_store_dwordx4 v131, v[156:159], s[48:49]
	s_add_u32 s48, s48, 0x1400
	s_addc_u32 s49, s49, 0
	s_add_u32 s8, s8, 0x400
	s_addc_u32 s9, s9, 0
	global_load_dwordx4 v[172:175], v132, s[8:9]
	global_load_dwordx4 v[176:179], v133, s[8:9]
	v_cvt_pk_bf16_f32 v152, v60, v61
	v_cvt_pk_bf16_f32 v153, v62, v63
	v_cvt_pk_bf16_f32 v154, v56, v57
	v_cvt_pk_bf16_f32 v155, v58, v59
	global_store_dwordx4 v130, v[152:155], s[6:7] sc1
	s_add_u32 s6, s6, s33
	s_addc_u32 s7, s7, 0
	s_waitcnt vmcnt(5)
	v_pk_mul_f32 v[162:163], v[52:53], v[168:169] op_sel:[1,0] op_sel_hi:[0,0]
	v_pk_fma_f32 v[52:53], v[52:53], v[164:165], v[162:163] op_sel:[0,0,0] op_sel_hi:[1,0,1] neg_lo:[0,0,1]
	v_pk_mul_f32 v[162:163], v[54:55], v[168:169] op_sel:[1,1] op_sel_hi:[0,1]
	v_pk_fma_f32 v[54:55], v[54:55], v[164:165], v[162:163] op_sel:[0,1,0] op_sel_hi:[1,1,1] neg_lo:[0,0,1]
	v_pk_mul_f32 v[162:163], v[48:49], v[170:171] op_sel:[1,0] op_sel_hi:[0,0]
	v_pk_fma_f32 v[48:49], v[48:49], v[166:167], v[162:163] op_sel:[0,0,0] op_sel_hi:[1,0,1] neg_lo:[0,0,1]
	v_pk_mul_f32 v[162:163], v[50:51], v[170:171] op_sel:[1,1] op_sel_hi:[0,1]
	v_pk_fma_f32 v[50:51], v[50:51], v[166:167], v[162:163] op_sel:[0,1,0] op_sel_hi:[1,1,1] neg_lo:[0,0,1]
	v_cvt_pk_bf16_f32 v156, v52, v53
	v_cvt_pk_bf16_f32 v157, v54, v55
	v_cvt_pk_bf16_f32 v158, v48, v49
	v_cvt_pk_bf16_f32 v159, v50, v51
	global_store_dwordx4 v131, v[156:159], s[48:49]
	s_add_u32 s48, s48, 0x400
	s_addc_u32 s49, s49, 0
	s_add_u32 s8, s8, 0x400
	s_addc_u32 s9, s9, 0
	global_load_dwordx4 v[164:167], v132, s[8:9]
	global_load_dwordx4 v[168:171], v133, s[8:9]
	v_cvt_pk_bf16_f32 v152, v44, v45
	v_cvt_pk_bf16_f32 v153, v46, v47
	v_cvt_pk_bf16_f32 v154, v40, v41
	v_cvt_pk_bf16_f32 v155, v42, v43
	global_store_dwordx4 v130, v[152:155], s[6:7] sc1
	s_add_u32 s6, s6, s33
	s_addc_u32 s7, s7, 0
	s_waitcnt vmcnt(5)
	v_pk_mul_f32 v[162:163], v[36:37], v[176:177] op_sel:[1,0] op_sel_hi:[0,0]
	v_pk_fma_f32 v[36:37], v[36:37], v[172:173], v[162:163] op_sel:[0,0,0] op_sel_hi:[1,0,1] neg_lo:[0,0,1]
	v_pk_mul_f32 v[162:163], v[38:39], v[176:177] op_sel:[1,1] op_sel_hi:[0,1]
	v_pk_fma_f32 v[38:39], v[38:39], v[172:173], v[162:163] op_sel:[0,1,0] op_sel_hi:[1,1,1] neg_lo:[0,0,1]
	v_pk_mul_f32 v[162:163], v[32:33], v[178:179] op_sel:[1,0] op_sel_hi:[0,0]
	v_pk_fma_f32 v[32:33], v[32:33], v[174:175], v[162:163] op_sel:[0,0,0] op_sel_hi:[1,0,1] neg_lo:[0,0,1]
	v_pk_mul_f32 v[162:163], v[34:35], v[178:179] op_sel:[1,1] op_sel_hi:[0,1]
	v_pk_fma_f32 v[34:35], v[34:35], v[174:175], v[162:163] op_sel:[0,1,0] op_sel_hi:[1,1,1] neg_lo:[0,0,1]
	v_cvt_pk_bf16_f32 v156, v36, v37
	v_cvt_pk_bf16_f32 v157, v38, v39
	v_cvt_pk_bf16_f32 v158, v32, v33
	v_cvt_pk_bf16_f32 v159, v34, v35
	global_store_dwordx4 v131, v[156:159], s[48:49]
	s_add_u32 s48, s48, 0x400
	s_addc_u32 s49, s49, 0
	s_add_u32 s8, s8, 0x400
	s_addc_u32 s9, s9, 0
	global_load_dwordx4 v[172:175], v132, s[8:9]
	global_load_dwordx4 v[176:179], v133, s[8:9]
	v_cvt_pk_bf16_f32 v152, v28, v29
	v_cvt_pk_bf16_f32 v153, v30, v31
	v_cvt_pk_bf16_f32 v154, v24, v25
	v_cvt_pk_bf16_f32 v155, v26, v27
	global_store_dwordx4 v130, v[152:155], s[6:7] sc1
	s_add_u32 s6, s6, s33
	s_addc_u32 s7, s7, 0
	s_waitcnt vmcnt(5)
	v_pk_mul_f32 v[162:163], v[20:21], v[168:169] op_sel:[1,0] op_sel_hi:[0,0]
	v_pk_fma_f32 v[20:21], v[20:21], v[164:165], v[162:163] op_sel:[0,0,0] op_sel_hi:[1,0,1] neg_lo:[0,0,1]
	v_pk_mul_f32 v[162:163], v[22:23], v[168:169] op_sel:[1,1] op_sel_hi:[0,1]
	v_pk_fma_f32 v[22:23], v[22:23], v[164:165], v[162:163] op_sel:[0,1,0] op_sel_hi:[1,1,1] neg_lo:[0,0,1]
	v_pk_mul_f32 v[162:163], v[16:17], v[170:171] op_sel:[1,0] op_sel_hi:[0,0]
	v_pk_fma_f32 v[16:17], v[16:17], v[166:167], v[162:163] op_sel:[0,0,0] op_sel_hi:[1,0,1] neg_lo:[0,0,1]
	v_pk_mul_f32 v[162:163], v[18:19], v[170:171] op_sel:[1,1] op_sel_hi:[0,1]
	v_pk_fma_f32 v[18:19], v[18:19], v[166:167], v[162:163] op_sel:[0,1,0] op_sel_hi:[1,1,1] neg_lo:[0,0,1]
	v_cvt_pk_bf16_f32 v156, v20, v21
	v_cvt_pk_bf16_f32 v157, v22, v23
	v_cvt_pk_bf16_f32 v158, v16, v17
	v_cvt_pk_bf16_f32 v159, v18, v19
	global_store_dwordx4 v131, v[156:159], s[48:49]
	s_add_u32 s48, s48, 0x400
	s_addc_u32 s49, s49, 0
	v_cvt_pk_bf16_f32 v152, v12, v13
	v_cvt_pk_bf16_f32 v153, v14, v15
	v_cvt_pk_bf16_f32 v154, v4, v5
	v_cvt_pk_bf16_f32 v155, v6, v7
	global_store_dwordx4 v130, v[152:155], s[6:7] sc1
	s_waitcnt vmcnt(3)
	v_pk_mul_f32 v[162:163], v[8:9], v[176:177] op_sel:[1,0] op_sel_hi:[0,0]
	v_pk_fma_f32 v[8:9], v[8:9], v[172:173], v[162:163] op_sel:[0,0,0] op_sel_hi:[1,0,1] neg_lo:[0,0,1]
	v_pk_mul_f32 v[162:163], v[10:11], v[176:177] op_sel:[1,1] op_sel_hi:[0,1]
	v_pk_fma_f32 v[10:11], v[10:11], v[172:173], v[162:163] op_sel:[0,1,0] op_sel_hi:[1,1,1] neg_lo:[0,0,1]
	v_pk_mul_f32 v[162:163], v[0:1], v[178:179] op_sel:[1,0] op_sel_hi:[0,0]
	v_pk_fma_f32 v[0:1], v[0:1], v[174:175], v[162:163] op_sel:[0,0,0] op_sel_hi:[1,0,1] neg_lo:[0,0,1]
	v_pk_mul_f32 v[162:163], v[2:3], v[178:179] op_sel:[1,1] op_sel_hi:[0,1]
	v_pk_fma_f32 v[2:3], v[2:3], v[174:175], v[162:163] op_sel:[0,1,0] op_sel_hi:[1,1,1] neg_lo:[0,0,1]
	v_cvt_pk_bf16_f32 v156, v8, v9
	v_cvt_pk_bf16_f32 v157, v10, v11
	v_cvt_pk_bf16_f32 v158, v0, v1
	v_cvt_pk_bf16_f32 v159, v2, v3
	global_store_dwordx4 v131, v[156:159], s[48:49]
	v_cndmask_b32_e64 v160, v136, v137, s[50:51]
	v_cndmask_b32_e64 v160, v160, v138, s[58:59]
	v_cndmask_b32_e64 v160, v160, v139, s[96:97]
	v_cndmask_b32_e64 v161, v140, v141, s[50:51]
	v_cndmask_b32_e64 v161, v161, v142, s[58:59]
	v_cndmask_b32_e64 v161, v161, v143, s[96:97]
	global_store_dword v134, v160, s[24:25] sc1
	s_add_u32 s24, s24, s35
	s_addc_u32 s25, s25, 0
	global_store_dword v134, v161, s[24:25] sc1
	s_branch .LBB0_872
.LBB0_872:
	s_mov_b64 s[4:5], 0
.LBB0_873:
	s_and_b64 vcc, exec, s[4:5]
	s_cbranch_vccz .LBB0_971
	s_load_dwordx2 s[4:5], s[0:1], 0xd0
	v_readlane_b32 s48, v254, 36
	v_readlane_b32 s49, v254, 45
	v_readlane_b32 s50, v255, 29
	v_lshlrev_b32_e32 v131, 5, v189
	s_lshl_b32 s51, s48, 8
	s_add_u32 s51, s51, s49
	s_lshl_b32 s35, s51, 5
	s_add_u32 s35, s35, 0x280000
	s_waitcnt lgkmcnt(0)
	s_add_u32 s24, s4, s35
	s_addc_u32 s25, s5, 0
	s_add_u32 s58, s24, 0x1000
	s_addc_u32 s59, s25, 0
	global_load_dwordx4 v[154:157], v131, s[24:25] offset:0
	global_load_dwordx4 v[158:161], v131, s[24:25] offset:16
	global_load_dwordx4 v[162:165], v131, s[24:25] offset:512
	global_load_dwordx4 v[166:169], v131, s[24:25] offset:528
	global_load_dwordx4 v[170:173], v131, s[24:25] offset:1024
	global_load_dwordx4 v[174:177], v131, s[24:25] offset:1040
	global_load_dwordx4 v[178:181], v131, s[24:25] offset:1536
	global_load_dwordx4 v[202:205], v131, s[24:25] offset:1552
	global_load_dwordx4 v[206:209], v131, s[58:59] offset:0
	global_load_dwordx4 v[210:213], v131, s[58:59] offset:16
	global_load_dwordx4 v[214:217], v131, s[58:59] offset:512
	global_load_dwordx4 v[218:221], v131, s[58:59] offset:528
	global_load_dwordx4 v[222:225], v131, s[58:59] offset:1024
	global_load_dwordx4 v[226:229], v131, s[58:59] offset:1040
	global_load_dwordx4 v[230:233], v131, s[58:59] offset:1536
	global_load_dwordx4 v[234:237], v131, s[58:59] offset:1552
	s_cmp_gt_u32 s74, 3
	s_cbranch_scc1 .Lq1_rope_tile
	s_lshl_b32 s35, s51, 11
	s_lshl_b32 s36, s74, 9
	s_add_u32 s35, s35, s36
	s_lshl_b32 s36, s50, 1
	s_add_u32 s35, s35, s36
	s_add_u32 s35, s35, 0x3c00000
	s_mov_b32 s33, 0x8000
	s_mov_b32 s34, 0x28000
	v_lshlrev_b32_e32 v130, 11, v189
	s_branch .Lq1_common
.Lq1_rope_tile:
	s_lshl_b32 s35, s51, 10
	s_sub_u32 s36, s74, 4
	s_lshl_b32 s36, s36, 9
	s_add_u32 s35, s35, s36
	s_lshl_b32 s36, s50, 1
	s_add_u32 s35, s35, s36
	s_add_u32 s35, s35, 0x5400000
	s_mov_b32 s33, 0x4000
	s_mov_b32 s34, 0x14000
	v_lshlrev_b32_e32 v130, 10, v189
.Lq1_common:
	v_lshl_add_u32 v130, v191, 4, v130
	s_add_u32 s6, s4, s35
	s_addc_u32 s7, s5, 0
	s_waitcnt vmcnt(0)
	v_add_f32_e32 v142, v154, v155
	v_add_f32_e32 v143, v156, v157
	v_add_f32_e32 v144, v158, v159
	v_add_f32_e32 v145, v160, v161
	v_add_f32_e32 v142, v142, v143
	v_add_f32_e32 v144, v144, v145
	v_add_f32_e32 v142, v142, v144
	v_fmamk_f32 v134, v142, 0x3b2aaaab, v242
	v_add_f32_e32 v142, v162, v163
	v_add_f32_e32 v143, v164, v165
	v_add_f32_e32 v144, v166, v167
	v_add_f32_e32 v145, v168, v169
	v_add_f32_e32 v142, v142, v143
	v_add_f32_e32 v144, v144, v145
	v_add_f32_e32 v142, v142, v144
	v_fmamk_f32 v135, v142, 0x3b2aaaab, v242
	v_add_f32_e32 v142, v170, v171
	v_add_f32_e32 v143, v172, v173
	v_add_f32_e32 v144, v174, v175
	v_add_f32_e32 v145, v176, v177
	v_add_f32_e32 v142, v142, v143
	v_add_f32_e32 v144, v144, v145
	v_add_f32_e32 v142, v142, v144
	v_fmamk_f32 v136, v142, 0x3b2aaaab, v242
	v_add_f32_e32 v142, v178, v179
	v_add_f32_e32 v143, v180, v181
	v_add_f32_e32 v144, v202, v203
	v_add_f32_e32 v145, v204, v205
	v_add_f32_e32 v142, v142, v143
	v_add_f32_e32 v144, v144, v145
	v_add_f32_e32 v142, v142, v144
	v_fmamk_f32 v137, v142, 0x3b2aaaab, v242
	v_add_f32_e32 v142, v206, v207
	v_add_f32_e32 v143, v208, v209
	v_add_f32_e32 v144, v210, v211
	v_add_f32_e32 v145, v212, v213
	v_add_f32_e32 v142, v142, v143
	v_add_f32_e32 v144, v144, v145
	v_add_f32_e32 v142, v142, v144
	v_fmamk_f32 v138, v142, 0x3b2aaaab, v242
	v_add_f32_e32 v142, v214, v215
	v_add_f32_e32 v143, v216, v217
	v_add_f32_e32 v144, v218, v219
	v_add_f32_e32 v145, v220, v221
	v_add_f32_e32 v142, v142, v143
	v_add_f32_e32 v144, v144, v145
	v_add_f32_e32 v142, v142, v144
	v_fmamk_f32 v139, v142, 0x3b2aaaab, v242
	v_add_f32_e32 v142, v222, v223
	v_add_f32_e32 v143, v224, v225
	v_add_f32_e32 v144, v226, v227
	v_add_f32_e32 v145, v228, v229
	v_add_f32_e32 v142, v142, v143
	v_add_f32_e32 v144, v144, v145
	v_add_f32_e32 v142, v142, v144
	v_fmamk_f32 v140, v142, 0x3b2aaaab, v242
	v_add_f32_e32 v142, v230, v231
	v_add_f32_e32 v143, v232, v233
	v_add_f32_e32 v144, v234, v235
	v_add_f32_e32 v145, v236, v237
	v_add_f32_e32 v142, v142, v143
	v_add_f32_e32 v144, v144, v145
	v_add_f32_e32 v142, v142, v144
	v_fmamk_f32 v141, v142, 0x3b2aaaab, v242
	v_rsq_f32_e32 v134, v134
	v_rsq_f32_e32 v135, v135
	v_rsq_f32_e32 v136, v136
	v_rsq_f32_e32 v137, v137
	v_rsq_f32_e32 v138, v138
	v_rsq_f32_e32 v139, v139
	v_rsq_f32_e32 v140, v140
	v_rsq_f32_e32 v141, v141
	s_nop 0
	v_mul_f32_e32 v134, 0x3e16c740, v134
	v_mul_f32_e32 v135, 0x3e16c740, v135
	v_mul_f32_e32 v136, 0x3e16c740, v136
	v_mul_f32_e32 v137, 0x3e16c740, v137
	v_mul_f32_e32 v138, 0x3e16c740, v138
	v_mul_f32_e32 v139, 0x3e16c740, v139
	v_mul_f32_e32 v140, 0x3e16c740, v140
	v_mul_f32_e32 v141, 0x3e16c740, v141
	s_cmp_lt_u32 s74, 4
	s_cbranch_scc1 .Lq1_plain
	s_cmp_lt_u32 s48, 32
	s_cbranch_scc1 .Lq1_plain
	s_sub_u32 s36, s48, 32
	s_and_b32 s36, s36, 3
	s_lshl_b32 s36, s36, 8
	s_add_u32 s36, s36, s49
	s_lshl_b32 s36, s36, 6
	s_add_u32 s36, s36, 0x1c0000
	s_add_u32 s8, s4, s36
	s_addc_u32 s9, s5, 0
	v_lshlrev_b32_e32 v132, 6, v189
	v_lshl_add_u32 v132, v191, 4, v132
	v_add_u32_e32 v133, 0x10000, v132
	global_load_dwordx4 v[218:221], v132, s[8:9]
	global_load_dwordx4 v[222:225], v133, s[8:9]
	s_add_u32 s8, s8, 0x400
	s_addc_u32 s9, s9, 0
	global_load_dwordx4 v[226:229], v132, s[8:9]
	global_load_dwordx4 v[230:233], v133, s[8:9]
	v_pk_mul_f32 v[126:127], v[126:127], v[134:135] op_sel_hi:[1,0]
	v_pk_mul_f32 v[128:129], v[128:129], v[134:135] op_sel_hi:[1,0]
	v_pk_mul_f32 v[122:123], v[122:123], v[134:135] op_sel_hi:[1,0]
	v_pk_mul_f32 v[124:125], v[124:125], v[134:135] op_sel_hi:[1,0]
	v_pk_mul_f32 v[118:119], v[118:119], v[134:135] op_sel_hi:[1,0]
	v_pk_mul_f32 v[120:121], v[120:121], v[134:135] op_sel_hi:[1,0]
	v_pk_mul_f32 v[114:115], v[114:115], v[134:135] op_sel_hi:[1,0]
	v_pk_mul_f32 v[116:117], v[116:117], v[134:135] op_sel_hi:[1,0]
	s_waitcnt vmcnt(2)
	v_pk_mul_f32 v[142:143], v[126:127], v[222:223] op_sel:[1,0] op_sel_hi:[0,0]
	v_pk_fma_f32 v[126:127], v[126:127], v[218:219], v[142:143] op_sel:[0,0,0] op_sel_hi:[1,0,1] neg_lo:[0,0,1]
	v_pk_mul_f32 v[142:143], v[128:129], v[222:223] op_sel:[1,1] op_sel_hi:[0,1]
	v_pk_fma_f32 v[128:129], v[128:129], v[218:219], v[142:143] op_sel:[0,1,0] op_sel_hi:[1,1,1] neg_lo:[0,0,1]
	v_pk_mul_f32 v[142:143], v[122:123], v[224:225] op_sel:[1,0] op_sel_hi:[0,0]
	v_pk_fma_f32 v[122:123], v[122:123], v[220:221], v[142:143] op_sel:[0,0,0] op_sel_hi:[1,0,1] neg_lo:[0,0,1]
	v_pk_mul_f32 v[142:143], v[124:125], v[224:225] op_sel:[1,1] op_sel_hi:[0,1]
	v_pk_fma_f32 v[124:125], v[124:125], v[220:221], v[142:143] op_sel:[0,1,0] op_sel_hi:[1,1,1] neg_lo:[0,0,1]
	v_cvt_pk_bf16_f32 v146, v126, v127
	v_cvt_pk_bf16_f32 v147, v128, v129
	v_cvt_pk_bf16_f32 v148, v122, v123
	v_cvt_pk_bf16_f32 v149, v124, v125
	global_store_dwordx4 v130, v[146:149], s[6:7]
	v_pk_mul_f32 v[142:143], v[118:119], v[222:223] op_sel:[1,0] op_sel_hi:[0,0]
	v_pk_fma_f32 v[118:119], v[118:119], v[218:219], v[142:143] op_sel:[0,0,0] op_sel_hi:[1,0,1] neg_lo:[0,0,1]
	v_pk_mul_f32 v[142:143], v[120:121], v[222:223] op_sel:[1,1] op_sel_hi:[0,1]
	v_pk_fma_f32 v[120:121], v[120:121], v[218:219], v[142:143] op_sel:[0,1,0] op_sel_hi:[1,1,1] neg_lo:[0,0,1]
	v_pk_mul_f32 v[142:143], v[114:115], v[224:225] op_sel:[1,0] op_sel_hi:[0,0]
	v_pk_fma_f32 v[114:115], v[114:115], v[220:221], v[142:143] op_sel:[0,0,0] op_sel_hi:[1,0,1] neg_lo:[0,0,1]
	v_pk_mul_f32 v[142:143], v[116:117], v[224:225] op_sel:[1,1] op_sel_hi:[0,1]
	v_pk_fma_f32 v[116:117], v[116:117], v[220:221], v[142:143] op_sel:[0,1,0] op_sel_hi:[1,1,1] neg_lo:[0,0,1]
	v_cvt_pk_bf16_f32 v150, v118, v119
	v_cvt_pk_bf16_f32 v151, v120, v121
	v_cvt_pk_bf16_f32 v152, v114, v115
	v_cvt_pk_bf16_f32 v153, v116, v117
	global_store_dwordx4 v130, v[150:153], s[6:7] offset:256
	s_add_u32 s6, s6, s33
	s_addc_u32 s7, s7, 0
	s_add_u32 s8, s8, 0x400
	s_addc_u32 s9, s9, 0
	global_load_dwordx4 v[218:221], v132, s[8:9]
	global_load_dwordx4 v[222:225], v133, s[8:9]
	v_pk_mul_f32 v[108:109], v[108:109], v[134:135] op_sel:[0,1] op_sel_hi:[1,1]
	v_pk_mul_f32 v[110:111], v[110:111], v[134:135] op_sel:[0,1] op_sel_hi:[1,1]
	v_pk_mul_f32 v[104:105], v[104:105], v[134:135] op_sel:[0,1] op_sel_hi:[1,1]
	v_pk_mul_f32 v[106:107], v[106:107], v[134:135] op_sel:[0,1] op_sel_hi:[1,1]
	v_pk_mul_f32 v[100:101], v[100:101], v[134:135] op_sel:[0,1] op_sel_hi:[1,1]
	v_pk_mul_f32 v[102:103], v[102:103], v[134:135] op_sel:[0,1] op_sel_hi:[1,1]
	v_pk_mul_f32 v[96:97], v[96:97], v[134:135] op_sel:[0,1] op_sel_hi:[1,1]
	v_pk_mul_f32 v[98:99], v[98:99], v[134:135] op_sel:[0,1] op_sel_hi:[1,1]
	s_waitcnt vmcnt(4)
	v_pk_mul_f32 v[142:143], v[108:109], v[230:231] op_sel:[1,0] op_sel_hi:[0,0]
	v_pk_fma_f32 v[108:109], v[108:109], v[226:227], v[142:143] op_sel:[0,0,0] op_sel_hi:[1,0,1] neg_lo:[0,0,1]
	v_pk_mul_f32 v[142:143], v[110:111], v[230:231] op_sel:[1,1] op_sel_hi:[0,1]
	v_pk_fma_f32 v[110:111], v[110:111], v[226:227], v[142:143] op_sel:[0,1,0] op_sel_hi:[1,1,1] neg_lo:[0,0,1]
	v_pk_mul_f32 v[142:143], v[104:105], v[232:233] op_sel:[1,0] op_sel_hi:[0,0]
	v_pk_fma_f32 v[104:105], v[104:105], v[228:229], v[142:143] op_sel:[0,0,0] op_sel_hi:[1,0,1] neg_lo:[0,0,1]
	v_pk_mul_f32 v[142:143], v[106:107], v[232:233] op_sel:[1,1] op_sel_hi:[0,1]
	v_pk_fma_f32 v[106:107], v[106:107], v[228:229], v[142:143] op_sel:[0,1,0] op_sel_hi:[1,1,1] neg_lo:[0,0,1]
	v_cvt_pk_bf16_f32 v146, v108, v109
	v_cvt_pk_bf16_f32 v147, v110, v111
	v_cvt_pk_bf16_f32 v148, v104, v105
	v_cvt_pk_bf16_f32 v149, v106, v107
	global_store_dwordx4 v130, v[146:149], s[6:7]
	v_pk_mul_f32 v[142:143], v[100:101], v[230:231] op_sel:[1,0] op_sel_hi:[0,0]
	v_pk_fma_f32 v[100:101], v[100:101], v[226:227], v[142:143] op_sel:[0,0,0] op_sel_hi:[1,0,1] neg_lo:[0,0,1]
	v_pk_mul_f32 v[142:143], v[102:103], v[230:231] op_sel:[1,1] op_sel_hi:[0,1]
	v_pk_fma_f32 v[102:103], v[102:103], v[226:227], v[142:143] op_sel:[0,1,0] op_sel_hi:[1,1,1] neg_lo:[0,0,1]
	v_pk_mul_f32 v[142:143], v[96:97], v[232:233] op_sel:[1,0] op_sel_hi:[0,0]
	v_pk_fma_f32 v[96:97], v[96:97], v[228:229], v[142:143] op_sel:[0,0,0] op_sel_hi:[1,0,1] neg_lo:[0,0,1]
	v_pk_mul_f32 v[142:143], v[98:99], v[232:233] op_sel:[1,1] op_sel_hi:[0,1]
	v_pk_fma_f32 v[98:99], v[98:99], v[228:229], v[142:143] op_sel:[0,1,0] op_sel_hi:[1,1,1] neg_lo:[0,0,1]
	v_cvt_pk_bf16_f32 v150, v100, v101
	v_cvt_pk_bf16_f32 v151, v102, v103
	v_cvt_pk_bf16_f32 v152, v96, v97
	v_cvt_pk_bf16_f32 v153, v98, v99
	global_store_dwordx4 v130, v[150:153], s[6:7] offset:256
	s_add_u32 s6, s6, s33
	s_addc_u32 s7, s7, 0
	s_add_u32 s8, s8, 0x400
	s_addc_u32 s9, s9, 0
	global_load_dwordx4 v[226:229], v132, s[8:9]
	global_load_dwordx4 v[230:233], v133, s[8:9]
	v_pk_mul_f32 v[92:93], v[92:93], v[136:137] op_sel_hi:[1,0]
	v_pk_mul_f32 v[94:95], v[94:95], v[136:137] op_sel_hi:[1,0]
	v_pk_mul_f32 v[88:89], v[88:89], v[136:137] op_sel_hi:[1,0]
	v_pk_mul_f32 v[90:91], v[90:91], v[136:137] op_sel_hi:[1,0]
	v_pk_mul_f32 v[84:85], v[84:85], v[136:137] op_sel_hi:[1,0]
	v_pk_mul_f32 v[86:87], v[86:87], v[136:137] op_sel_hi:[1,0]
	v_pk_mul_f32 v[80:81], v[80:81], v[136:137] op_sel_hi:[1,0]
	v_pk_mul_f32 v[82:83], v[82:83], v[136:137] op_sel_hi:[1,0]
	s_waitcnt vmcnt(4)
	v_pk_mul_f32 v[142:143], v[92:93], v[222:223] op_sel:[1,0] op_sel_hi:[0,0]
	v_pk_fma_f32 v[92:93], v[92:93], v[218:219], v[142:143] op_sel:[0,0,0] op_sel_hi:[1,0,1] neg_lo:[0,0,1]
	v_pk_mul_f32 v[142:143], v[94:95], v[222:223] op_sel:[1,1] op_sel_hi:[0,1]
	v_pk_fma_f32 v[94:95], v[94:95], v[218:219], v[142:143] op_sel:[0,1,0] op_sel_hi:[1,1,1] neg_lo:[0,0,1]
	v_pk_mul_f32 v[142:143], v[88:89], v[224:225] op_sel:[1,0] op_sel_hi:[0,0]
	v_pk_fma_f32 v[88:89], v[88:89], v[220:221], v[142:143] op_sel:[0,0,0] op_sel_hi:[1,0,1] neg_lo:[0,0,1]
	v_pk_mul_f32 v[142:143], v[90:91], v[224:225] op_sel:[1,1] op_sel_hi:[0,1]
	v_pk_fma_f32 v[90:91], v[90:91], v[220:221], v[142:143] op_sel:[0,1,0] op_sel_hi:[1,1,1] neg_lo:[0,0,1]
	v_cvt_pk_bf16_f32 v146, v92, v93
	v_cvt_pk_bf16_f32 v147, v94, v95
	v_cvt_pk_bf16_f32 v148, v88, v89
	v_cvt_pk_bf16_f32 v149, v90, v91
	global_store_dwordx4 v130, v[146:149], s[6:7]
	v_pk_mul_f32 v[142:143], v[84:85], v[222:223] op_sel:[1,0] op_sel_hi:[0,0]
	v_pk_fma_f32 v[84:85], v[84:85], v[218:219], v[142:143] op_sel:[0,0,0] op_sel_hi:[1,0,1] neg_lo:[0,0,1]
	v_pk_mul_f32 v[142:143], v[86:87], v[222:223] op_sel:[1,1] op_sel_hi:[0,1]
	v_pk_fma_f32 v[86:87], v[86:87], v[218:219], v[142:143] op_sel:[0,1,0] op_sel_hi:[1,1,1] neg_lo:[0,0,1]
	v_pk_mul_f32 v[142:143], v[80:81], v[224:225] op_sel:[1,0] op_sel_hi:[0,0]
	v_pk_fma_f32 v[80:81], v[80:81], v[220:221], v[142:143] op_sel:[0,0,0] op_sel_hi:[1,0,1] neg_lo:[0,0,1]
	v_pk_mul_f32 v[142:143], v[82:83], v[224:225] op_sel:[1,1] op_sel_hi:[0,1]
	v_pk_fma_f32 v[82:83], v[82:83], v[220:221], v[142:143] op_sel:[0,1,0] op_sel_hi:[1,1,1] neg_lo:[0,0,1]
	v_cvt_pk_bf16_f32 v150, v84, v85
	v_cvt_pk_bf16_f32 v151, v86, v87
	v_cvt_pk_bf16_f32 v152, v80, v81
	v_cvt_pk_bf16_f32 v153, v82, v83
	global_store_dwordx4 v130, v[150:153], s[6:7] offset:256
	s_add_u32 s6, s6, s33
	s_addc_u32 s7, s7, 0
	s_add_u32 s8, s8, 0x1400
	s_addc_u32 s9, s9, 0
	global_load_dwordx4 v[218:221], v132, s[8:9]
	global_load_dwordx4 v[222:225], v133, s[8:9]
	v_pk_mul_f32 v[76:77], v[76:77], v[136:137] op_sel:[0,1] op_sel_hi:[1,1]
	v_pk_mul_f32 v[78:79], v[78:79], v[136:137] op_sel:[0,1] op_sel_hi:[1,1]
	v_pk_mul_f32 v[72:73], v[72:73], v[136:137] op_sel:[0,1] op_sel_hi:[1,1]
	v_pk_mul_f32 v[74:75], v[74:75], v[136:137] op_sel:[0,1] op_sel_hi:[1,1]
	v_pk_mul_f32 v[68:69], v[68:69], v[136:137] op_sel:[0,1] op_sel_hi:[1,1]
	v_pk_mul_f32 v[70:71], v[70:71], v[136:137] op_sel:[0,1] op_sel_hi:[1,1]
	v_pk_mul_f32 v[64:65], v[64:65], v[136:137] op_sel:[0,1] op_sel_hi:[1,1]
	v_pk_mul_f32 v[66:67], v[66:67], v[136:137] op_sel:[0,1] op_sel_hi:[1,1]
	s_waitcnt vmcnt(4)
	v_pk_mul_f32 v[142:143], v[76:77], v[230:231] op_sel:[1,0] op_sel_hi:[0,0]
	v_pk_fma_f32 v[76:77], v[76:77], v[226:227], v[142:143] op_sel:[0,0,0] op_sel_hi:[1,0,1] neg_lo:[0,0,1]
	v_pk_mul_f32 v[142:143], v[78:79], v[230:231] op_sel:[1,1] op_sel_hi:[0,1]
	v_pk_fma_f32 v[78:79], v[78:79], v[226:227], v[142:143] op_sel:[0,1,0] op_sel_hi:[1,1,1] neg_lo:[0,0,1]
	v_pk_mul_f32 v[142:143], v[72:73], v[232:233] op_sel:[1,0] op_sel_hi:[0,0]
	v_pk_fma_f32 v[72:73], v[72:73], v[228:229], v[142:143] op_sel:[0,0,0] op_sel_hi:[1,0,1] neg_lo:[0,0,1]
	v_pk_mul_f32 v[142:143], v[74:75], v[232:233] op_sel:[1,1] op_sel_hi:[0,1]
	v_pk_fma_f32 v[74:75], v[74:75], v[228:229], v[142:143] op_sel:[0,1,0] op_sel_hi:[1,1,1] neg_lo:[0,0,1]
	v_cvt_pk_bf16_f32 v146, v76, v77
	v_cvt_pk_bf16_f32 v147, v78, v79
	v_cvt_pk_bf16_f32 v148, v72, v73
	v_cvt_pk_bf16_f32 v149, v74, v75
	global_store_dwordx4 v130, v[146:149], s[6:7]
	v_pk_mul_f32 v[142:143], v[68:69], v[230:231] op_sel:[1,0] op_sel_hi:[0,0]
	v_pk_fma_f32 v[68:69], v[68:69], v[226:227], v[142:143] op_sel:[0,0,0] op_sel_hi:[1,0,1] neg_lo:[0,0,1]
	v_pk_mul_f32 v[142:143], v[70:71], v[230:231] op_sel:[1,1] op_sel_hi:[0,1]
	v_pk_fma_f32 v[70:71], v[70:71], v[226:227], v[142:143] op_sel:[0,1,0] op_sel_hi:[1,1,1] neg_lo:[0,0,1]
	v_pk_mul_f32 v[142:143], v[64:65], v[232:233] op_sel:[1,0] op_sel_hi:[0,0]
	v_pk_fma_f32 v[64:65], v[64:65], v[228:229], v[142:143] op_sel:[0,0,0] op_sel_hi:[1,0,1] neg_lo:[0,0,1]
	v_pk_mul_f32 v[142:143], v[66:67], v[232:233] op_sel:[1,1] op_sel_hi:[0,1]
	v_pk_fma_f32 v[66:67], v[66:67], v[228:229], v[142:143] op_sel:[0,1,0] op_sel_hi:[1,1,1] neg_lo:[0,0,1]
	v_cvt_pk_bf16_f32 v150, v68, v69
	v_cvt_pk_bf16_f32 v151, v70, v71
	v_cvt_pk_bf16_f32 v152, v64, v65
	v_cvt_pk_bf16_f32 v153, v66, v67
	global_store_dwordx4 v130, v[150:153], s[6:7] offset:256
	s_add_u32 s6, s6, s34
	s_addc_u32 s7, s7, 0
	s_add_u32 s8, s8, 0x400
	s_addc_u32 s9, s9, 0
	global_load_dwordx4 v[226:229], v132, s[8:9]
	global_load_dwordx4 v[230:233], v133, s[8:9]
	v_pk_mul_f32 v[60:61], v[60:61], v[138:139] op_sel_hi:[1,0]
	v_pk_mul_f32 v[62:63], v[62:63], v[138:139] op_sel_hi:[1,0]
	v_pk_mul_f32 v[56:57], v[56:57], v[138:139] op_sel_hi:[1,0]
	v_pk_mul_f32 v[58:59], v[58:59], v[138:139] op_sel_hi:[1,0]
	v_pk_mul_f32 v[52:53], v[52:53], v[138:139] op_sel_hi:[1,0]
	v_pk_mul_f32 v[54:55], v[54:55], v[138:139] op_sel_hi:[1,0]
	v_pk_mul_f32 v[48:49], v[48:49], v[138:139] op_sel_hi:[1,0]
	v_pk_mul_f32 v[50:51], v[50:51], v[138:139] op_sel_hi:[1,0]
	s_waitcnt vmcnt(4)
	v_pk_mul_f32 v[142:143], v[60:61], v[222:223] op_sel:[1,0] op_sel_hi:[0,0]
	v_pk_fma_f32 v[60:61], v[60:61], v[218:219], v[142:143] op_sel:[0,0,0] op_sel_hi:[1,0,1] neg_lo:[0,0,1]
	v_pk_mul_f32 v[142:143], v[62:63], v[222:223] op_sel:[1,1] op_sel_hi:[0,1]
	v_pk_fma_f32 v[62:63], v[62:63], v[218:219], v[142:143] op_sel:[0,1,0] op_sel_hi:[1,1,1] neg_lo:[0,0,1]
	v_pk_mul_f32 v[142:143], v[56:57], v[224:225] op_sel:[1,0] op_sel_hi:[0,0]
	v_pk_fma_f32 v[56:57], v[56:57], v[220:221], v[142:143] op_sel:[0,0,0] op_sel_hi:[1,0,1] neg_lo:[0,0,1]
	v_pk_mul_f32 v[142:143], v[58:59], v[224:225] op_sel:[1,1] op_sel_hi:[0,1]
	v_pk_fma_f32 v[58:59], v[58:59], v[220:221], v[142:143] op_sel:[0,1,0] op_sel_hi:[1,1,1] neg_lo:[0,0,1]
	v_cvt_pk_bf16_f32 v146, v60, v61
	v_cvt_pk_bf16_f32 v147, v62, v63
	v_cvt_pk_bf16_f32 v148, v56, v57
	v_cvt_pk_bf16_f32 v149, v58, v59
	global_store_dwordx4 v130, v[146:149], s[6:7]
	v_pk_mul_f32 v[142:143], v[52:53], v[222:223] op_sel:[1,0] op_sel_hi:[0,0]
	v_pk_fma_f32 v[52:53], v[52:53], v[218:219], v[142:143] op_sel:[0,0,0] op_sel_hi:[1,0,1] neg_lo:[0,0,1]
	v_pk_mul_f32 v[142:143], v[54:55], v[222:223] op_sel:[1,1] op_sel_hi:[0,1]
	v_pk_fma_f32 v[54:55], v[54:55], v[218:219], v[142:143] op_sel:[0,1,0] op_sel_hi:[1,1,1] neg_lo:[0,0,1]
	v_pk_mul_f32 v[142:143], v[48:49], v[224:225] op_sel:[1,0] op_sel_hi:[0,0]
	v_pk_fma_f32 v[48:49], v[48:49], v[220:221], v[142:143] op_sel:[0,0,0] op_sel_hi:[1,0,1] neg_lo:[0,0,1]
	v_pk_mul_f32 v[142:143], v[50:51], v[224:225] op_sel:[1,1] op_sel_hi:[0,1]
	v_pk_fma_f32 v[50:51], v[50:51], v[220:221], v[142:143] op_sel:[0,1,0] op_sel_hi:[1,1,1] neg_lo:[0,0,1]
	v_cvt_pk_bf16_f32 v150, v52, v53
	v_cvt_pk_bf16_f32 v151, v54, v55
	v_cvt_pk_bf16_f32 v152, v48, v49
	v_cvt_pk_bf16_f32 v153, v50, v51
	global_store_dwordx4 v130, v[150:153], s[6:7] offset:256
	s_add_u32 s6, s6, s33
	s_addc_u32 s7, s7, 0
	s_add_u32 s8, s8, 0x400
	s_addc_u32 s9, s9, 0
	global_load_dwordx4 v[218:221], v132, s[8:9]
	global_load_dwordx4 v[222:225], v133, s[8:9]
	v_pk_mul_f32 v[44:45], v[44:45], v[138:139] op_sel:[0,1] op_sel_hi:[1,1]
	v_pk_mul_f32 v[46:47], v[46:47], v[138:139] op_sel:[0,1] op_sel_hi:[1,1]
	v_pk_mul_f32 v[40:41], v[40:41], v[138:139] op_sel:[0,1] op_sel_hi:[1,1]
	v_pk_mul_f32 v[42:43], v[42:43], v[138:139] op_sel:[0,1] op_sel_hi:[1,1]
	v_pk_mul_f32 v[36:37], v[36:37], v[138:139] op_sel:[0,1] op_sel_hi:[1,1]
	v_pk_mul_f32 v[38:39], v[38:39], v[138:139] op_sel:[0,1] op_sel_hi:[1,1]
	v_pk_mul_f32 v[32:33], v[32:33], v[138:139] op_sel:[0,1] op_sel_hi:[1,1]
	v_pk_mul_f32 v[34:35], v[34:35], v[138:139] op_sel:[0,1] op_sel_hi:[1,1]
	s_waitcnt vmcnt(4)
	v_pk_mul_f32 v[142:143], v[44:45], v[230:231] op_sel:[1,0] op_sel_hi:[0,0]
	v_pk_fma_f32 v[44:45], v[44:45], v[226:227], v[142:143] op_sel:[0,0,0] op_sel_hi:[1,0,1] neg_lo:[0,0,1]
	v_pk_mul_f32 v[142:143], v[46:47], v[230:231] op_sel:[1,1] op_sel_hi:[0,1]
	v_pk_fma_f32 v[46:47], v[46:47], v[226:227], v[142:143] op_sel:[0,1,0] op_sel_hi:[1,1,1] neg_lo:[0,0,1]
	v_pk_mul_f32 v[142:143], v[40:41], v[232:233] op_sel:[1,0] op_sel_hi:[0,0]
	v_pk_fma_f32 v[40:41], v[40:41], v[228:229], v[142:143] op_sel:[0,0,0] op_sel_hi:[1,0,1] neg_lo:[0,0,1]
	v_pk_mul_f32 v[142:143], v[42:43], v[232:233] op_sel:[1,1] op_sel_hi:[0,1]
	v_pk_fma_f32 v[42:43], v[42:43], v[228:229], v[142:143] op_sel:[0,1,0] op_sel_hi:[1,1,1] neg_lo:[0,0,1]
	v_cvt_pk_bf16_f32 v146, v44, v45
	v_cvt_pk_bf16_f32 v147, v46, v47
	v_cvt_pk_bf16_f32 v148, v40, v41
	v_cvt_pk_bf16_f32 v149, v42, v43
	global_store_dwordx4 v130, v[146:149], s[6:7]
	v_pk_mul_f32 v[142:143], v[36:37], v[230:231] op_sel:[1,0] op_sel_hi:[0,0]
	v_pk_fma_f32 v[36:37], v[36:37], v[226:227], v[142:143] op_sel:[0,0,0] op_sel_hi:[1,0,1] neg_lo:[0,0,1]
	v_pk_mul_f32 v[142:143], v[38:39], v[230:231] op_sel:[1,1] op_sel_hi:[0,1]
	v_pk_fma_f32 v[38:39], v[38:39], v[226:227], v[142:143] op_sel:[0,1,0] op_sel_hi:[1,1,1] neg_lo:[0,0,1]
	v_pk_mul_f32 v[142:143], v[32:33], v[232:233] op_sel:[1,0] op_sel_hi:[0,0]
	v_pk_fma_f32 v[32:33], v[32:33], v[228:229], v[142:143] op_sel:[0,0,0] op_sel_hi:[1,0,1] neg_lo:[0,0,1]
	v_pk_mul_f32 v[142:143], v[34:35], v[232:233] op_sel:[1,1] op_sel_hi:[0,1]
	v_pk_fma_f32 v[34:35], v[34:35], v[228:229], v[142:143] op_sel:[0,1,0] op_sel_hi:[1,1,1] neg_lo:[0,0,1]
	v_cvt_pk_bf16_f32 v150, v36, v37
	v_cvt_pk_bf16_f32 v151, v38, v39
	v_cvt_pk_bf16_f32 v152, v32, v33
	v_cvt_pk_bf16_f32 v153, v34, v35
	global_store_dwordx4 v130, v[150:153], s[6:7] offset:256
	s_add_u32 s6, s6, s33
	s_addc_u32 s7, s7, 0
	s_add_u32 s8, s8, 0x400
	s_addc_u32 s9, s9, 0
	global_load_dwordx4 v[226:229], v132, s[8:9]
	global_load_dwordx4 v[230:233], v133, s[8:9]
	v_pk_mul_f32 v[28:29], v[28:29], v[140:141] op_sel_hi:[1,0]
	v_pk_mul_f32 v[30:31], v[30:31], v[140:141] op_sel_hi:[1,0]
	v_pk_mul_f32 v[24:25], v[24:25], v[140:141] op_sel_hi:[1,0]
	v_pk_mul_f32 v[26:27], v[26:27], v[140:141] op_sel_hi:[1,0]
	v_pk_mul_f32 v[20:21], v[20:21], v[140:141] op_sel_hi:[1,0]
	v_pk_mul_f32 v[22:23], v[22:23], v[140:141] op_sel_hi:[1,0]
	v_pk_mul_f32 v[16:17], v[16:17], v[140:141] op_sel_hi:[1,0]
	v_pk_mul_f32 v[18:19], v[18:19], v[140:141] op_sel_hi:[1,0]
	s_waitcnt vmcnt(4)
	v_pk_mul_f32 v[142:143], v[28:29], v[222:223] op_sel:[1,0] op_sel_hi:[0,0]
	v_pk_fma_f32 v[28:29], v[28:29], v[218:219], v[142:143] op_sel:[0,0,0] op_sel_hi:[1,0,1] neg_lo:[0,0,1]
	v_pk_mul_f32 v[142:143], v[30:31], v[222:223] op_sel:[1,1] op_sel_hi:[0,1]
	v_pk_fma_f32 v[30:31], v[30:31], v[218:219], v[142:143] op_sel:[0,1,0] op_sel_hi:[1,1,1] neg_lo:[0,0,1]
	v_pk_mul_f32 v[142:143], v[24:25], v[224:225] op_sel:[1,0] op_sel_hi:[0,0]
	v_pk_fma_f32 v[24:25], v[24:25], v[220:221], v[142:143] op_sel:[0,0,0] op_sel_hi:[1,0,1] neg_lo:[0,0,1]
	v_pk_mul_f32 v[142:143], v[26:27], v[224:225] op_sel:[1,1] op_sel_hi:[0,1]
	v_pk_fma_f32 v[26:27], v[26:27], v[220:221], v[142:143] op_sel:[0,1,0] op_sel_hi:[1,1,1] neg_lo:[0,0,1]
	v_cvt_pk_bf16_f32 v146, v28, v29
	v_cvt_pk_bf16_f32 v147, v30, v31
	v_cvt_pk_bf16_f32 v148, v24, v25
	v_cvt_pk_bf16_f32 v149, v26, v27
	global_store_dwordx4 v130, v[146:149], s[6:7]
	v_pk_mul_f32 v[142:143], v[20:21], v[222:223] op_sel:[1,0] op_sel_hi:[0,0]
	v_pk_fma_f32 v[20:21], v[20:21], v[218:219], v[142:143] op_sel:[0,0,0] op_sel_hi:[1,0,1] neg_lo:[0,0,1]
	v_pk_mul_f32 v[142:143], v[22:23], v[222:223] op_sel:[1,1] op_sel_hi:[0,1]
	v_pk_fma_f32 v[22:23], v[22:23], v[218:219], v[142:143] op_sel:[0,1,0] op_sel_hi:[1,1,1] neg_lo:[0,0,1]
	v_pk_mul_f32 v[142:143], v[16:17], v[224:225] op_sel:[1,0] op_sel_hi:[0,0]
	v_pk_fma_f32 v[16:17], v[16:17], v[220:221], v[142:143] op_sel:[0,0,0] op_sel_hi:[1,0,1] neg_lo:[0,0,1]
	v_pk_mul_f32 v[142:143], v[18:19], v[224:225] op_sel:[1,1] op_sel_hi:[0,1]
	v_pk_fma_f32 v[18:19], v[18:19], v[220:221], v[142:143] op_sel:[0,1,0] op_sel_hi:[1,1,1] neg_lo:[0,0,1]
	v_cvt_pk_bf16_f32 v150, v20, v21
	v_cvt_pk_bf16_f32 v151, v22, v23
	v_cvt_pk_bf16_f32 v152, v16, v17
	v_cvt_pk_bf16_f32 v153, v18, v19
	global_store_dwordx4 v130, v[150:153], s[6:7] offset:256
	s_add_u32 s6, s6, s33
	s_addc_u32 s7, s7, 0
	v_pk_mul_f32 v[12:13], v[12:13], v[140:141] op_sel:[0,1] op_sel_hi:[1,1]
	v_pk_mul_f32 v[14:15], v[14:15], v[140:141] op_sel:[0,1] op_sel_hi:[1,1]
	v_pk_mul_f32 v[4:5], v[4:5], v[140:141] op_sel:[0,1] op_sel_hi:[1,1]
	v_pk_mul_f32 v[6:7], v[6:7], v[140:141] op_sel:[0,1] op_sel_hi:[1,1]
	v_pk_mul_f32 v[8:9], v[8:9], v[140:141] op_sel:[0,1] op_sel_hi:[1,1]
	v_pk_mul_f32 v[10:11], v[10:11], v[140:141] op_sel:[0,1] op_sel_hi:[1,1]
	v_pk_mul_f32 v[0:1], v[0:1], v[140:141] op_sel:[0,1] op_sel_hi:[1,1]
	v_pk_mul_f32 v[2:3], v[2:3], v[140:141] op_sel:[0,1] op_sel_hi:[1,1]
	s_waitcnt vmcnt(2)
	v_pk_mul_f32 v[142:143], v[12:13], v[230:231] op_sel:[1,0] op_sel_hi:[0,0]
	v_pk_fma_f32 v[12:13], v[12:13], v[226:227], v[142:143] op_sel:[0,0,0] op_sel_hi:[1,0,1] neg_lo:[0,0,1]
	v_pk_mul_f32 v[142:143], v[14:15], v[230:231] op_sel:[1,1] op_sel_hi:[0,1]
	v_pk_fma_f32 v[14:15], v[14:15], v[226:227], v[142:143] op_sel:[0,1,0] op_sel_hi:[1,1,1] neg_lo:[0,0,1]
	v_pk_mul_f32 v[142:143], v[4:5], v[232:233] op_sel:[1,0] op_sel_hi:[0,0]
	v_pk_fma_f32 v[4:5], v[4:5], v[228:229], v[142:143] op_sel:[0,0,0] op_sel_hi:[1,0,1] neg_lo:[0,0,1]
	v_pk_mul_f32 v[142:143], v[6:7], v[232:233] op_sel:[1,1] op_sel_hi:[0,1]
	v_pk_fma_f32 v[6:7], v[6:7], v[228:229], v[142:143] op_sel:[0,1,0] op_sel_hi:[1,1,1] neg_lo:[0,0,1]
	v_cvt_pk_bf16_f32 v146, v12, v13
	v_cvt_pk_bf16_f32 v147, v14, v15
	v_cvt_pk_bf16_f32 v148, v4, v5
	v_cvt_pk_bf16_f32 v149, v6, v7
	global_store_dwordx4 v130, v[146:149], s[6:7]
	v_pk_mul_f32 v[142:143], v[8:9], v[230:231] op_sel:[1,0] op_sel_hi:[0,0]
	v_pk_fma_f32 v[8:9], v[8:9], v[226:227], v[142:143] op_sel:[0,0,0] op_sel_hi:[1,0,1] neg_lo:[0,0,1]
	v_pk_mul_f32 v[142:143], v[10:11], v[230:231] op_sel:[1,1] op_sel_hi:[0,1]
	v_pk_fma_f32 v[10:11], v[10:11], v[226:227], v[142:143] op_sel:[0,1,0] op_sel_hi:[1,1,1] neg_lo:[0,0,1]
	v_pk_mul_f32 v[142:143], v[0:1], v[232:233] op_sel:[1,0] op_sel_hi:[0,0]
	v_pk_fma_f32 v[0:1], v[0:1], v[228:229], v[142:143] op_sel:[0,0,0] op_sel_hi:[1,0,1] neg_lo:[0,0,1]
	v_pk_mul_f32 v[142:143], v[2:3], v[232:233] op_sel:[1,1] op_sel_hi:[0,1]
	v_pk_fma_f32 v[2:3], v[2:3], v[228:229], v[142:143] op_sel:[0,1,0] op_sel_hi:[1,1,1] neg_lo:[0,0,1]
	v_cvt_pk_bf16_f32 v150, v8, v9
	v_cvt_pk_bf16_f32 v151, v10, v11
	v_cvt_pk_bf16_f32 v152, v0, v1
	v_cvt_pk_bf16_f32 v153, v2, v3
	global_store_dwordx4 v130, v[150:153], s[6:7] offset:256
	s_branch .LBB0_971
.Lq1_plain:
	v_pk_mul_f32 v[126:127], v[126:127], v[134:135] op_sel_hi:[1,0]
	v_pk_mul_f32 v[128:129], v[128:129], v[134:135] op_sel_hi:[1,0]
	v_pk_mul_f32 v[122:123], v[122:123], v[134:135] op_sel_hi:[1,0]
	v_pk_mul_f32 v[124:125], v[124:125], v[134:135] op_sel_hi:[1,0]
	v_pk_mul_f32 v[118:119], v[118:119], v[134:135] op_sel_hi:[1,0]
	v_pk_mul_f32 v[120:121], v[120:121], v[134:135] op_sel_hi:[1,0]
	v_pk_mul_f32 v[114:115], v[114:115], v[134:135] op_sel_hi:[1,0]
	v_pk_mul_f32 v[116:117], v[116:117], v[134:135] op_sel_hi:[1,0]
	v_cvt_pk_bf16_f32 v146, v126, v127
	v_cvt_pk_bf16_f32 v147, v128, v129
	v_cvt_pk_bf16_f32 v148, v122, v123
	v_cvt_pk_bf16_f32 v149, v124, v125
	global_store_dwordx4 v130, v[146:149], s[6:7]
	v_cvt_pk_bf16_f32 v150, v118, v119
	v_cvt_pk_bf16_f32 v151, v120, v121
	v_cvt_pk_bf16_f32 v152, v114, v115
	v_cvt_pk_bf16_f32 v153, v116, v117
	global_store_dwordx4 v130, v[150:153], s[6:7] offset:256
	s_add_u32 s6, s6, s33
	s_addc_u32 s7, s7, 0
	v_pk_mul_f32 v[108:109], v[108:109], v[134:135] op_sel:[0,1] op_sel_hi:[1,1]
	v_pk_mul_f32 v[110:111], v[110:111], v[134:135] op_sel:[0,1] op_sel_hi:[1,1]
	v_pk_mul_f32 v[104:105], v[104:105], v[134:135] op_sel:[0,1] op_sel_hi:[1,1]
	v_pk_mul_f32 v[106:107], v[106:107], v[134:135] op_sel:[0,1] op_sel_hi:[1,1]
	v_pk_mul_f32 v[100:101], v[100:101], v[134:135] op_sel:[0,1] op_sel_hi:[1,1]
	v_pk_mul_f32 v[102:103], v[102:103], v[134:135] op_sel:[0,1] op_sel_hi:[1,1]
	v_pk_mul_f32 v[96:97], v[96:97], v[134:135] op_sel:[0,1] op_sel_hi:[1,1]
	v_pk_mul_f32 v[98:99], v[98:99], v[134:135] op_sel:[0,1] op_sel_hi:[1,1]
	v_cvt_pk_bf16_f32 v146, v108, v109
	v_cvt_pk_bf16_f32 v147, v110, v111
	v_cvt_pk_bf16_f32 v148, v104, v105
	v_cvt_pk_bf16_f32 v149, v106, v107
	global_store_dwordx4 v130, v[146:149], s[6:7]
	v_cvt_pk_bf16_f32 v150, v100, v101
	v_cvt_pk_bf16_f32 v151, v102, v103
	v_cvt_pk_bf16_f32 v152, v96, v97
	v_cvt_pk_bf16_f32 v153, v98, v99
	global_store_dwordx4 v130, v[150:153], s[6:7] offset:256
	s_add_u32 s6, s6, s33
	s_addc_u32 s7, s7, 0
	v_pk_mul_f32 v[92:93], v[92:93], v[136:137] op_sel_hi:[1,0]
	v_pk_mul_f32 v[94:95], v[94:95], v[136:137] op_sel_hi:[1,0]
	v_pk_mul_f32 v[88:89], v[88:89], v[136:137] op_sel_hi:[1,0]
	v_pk_mul_f32 v[90:91], v[90:91], v[136:137] op_sel_hi:[1,0]
	v_pk_mul_f32 v[84:85], v[84:85], v[136:137] op_sel_hi:[1,0]
	v_pk_mul_f32 v[86:87], v[86:87], v[136:137] op_sel_hi:[1,0]
	v_pk_mul_f32 v[80:81], v[80:81], v[136:137] op_sel_hi:[1,0]
	v_pk_mul_f32 v[82:83], v[82:83], v[136:137] op_sel_hi:[1,0]
	v_cvt_pk_bf16_f32 v146, v92, v93
	v_cvt_pk_bf16_f32 v147, v94, v95
	v_cvt_pk_bf16_f32 v148, v88, v89
	v_cvt_pk_bf16_f32 v149, v90, v91
	global_store_dwordx4 v130, v[146:149], s[6:7]
	v_cvt_pk_bf16_f32 v150, v84, v85
	v_cvt_pk_bf16_f32 v151, v86, v87
	v_cvt_pk_bf16_f32 v152, v80, v81
	v_cvt_pk_bf16_f32 v153, v82, v83
	global_store_dwordx4 v130, v[150:153], s[6:7] offset:256
	s_add_u32 s6, s6, s33
	s_addc_u32 s7, s7, 0
	v_pk_mul_f32 v[76:77], v[76:77], v[136:137] op_sel:[0,1] op_sel_hi:[1,1]
	v_pk_mul_f32 v[78:79], v[78:79], v[136:137] op_sel:[0,1] op_sel_hi:[1,1]
	v_pk_mul_f32 v[72:73], v[72:73], v[136:137] op_sel:[0,1] op_sel_hi:[1,1]
	v_pk_mul_f32 v[74:75], v[74:75], v[136:137] op_sel:[0,1] op_sel_hi:[1,1]
	v_pk_mul_f32 v[68:69], v[68:69], v[136:137] op_sel:[0,1] op_sel_hi:[1,1]
	v_pk_mul_f32 v[70:71], v[70:71], v[136:137] op_sel:[0,1] op_sel_hi:[1,1]
	v_pk_mul_f32 v[64:65], v[64:65], v[136:137] op_sel:[0,1] op_sel_hi:[1,1]
	v_pk_mul_f32 v[66:67], v[66:67], v[136:137] op_sel:[0,1] op_sel_hi:[1,1]
	v_cvt_pk_bf16_f32 v146, v76, v77
	v_cvt_pk_bf16_f32 v147, v78, v79
	v_cvt_pk_bf16_f32 v148, v72, v73
	v_cvt_pk_bf16_f32 v149, v74, v75
	global_store_dwordx4 v130, v[146:149], s[6:7]
	v_cvt_pk_bf16_f32 v150, v68, v69
	v_cvt_pk_bf16_f32 v151, v70, v71
	v_cvt_pk_bf16_f32 v152, v64, v65
	v_cvt_pk_bf16_f32 v153, v66, v67
	global_store_dwordx4 v130, v[150:153], s[6:7] offset:256
	s_add_u32 s6, s6, s34
	s_addc_u32 s7, s7, 0
	v_pk_mul_f32 v[60:61], v[60:61], v[138:139] op_sel_hi:[1,0]
	v_pk_mul_f32 v[62:63], v[62:63], v[138:139] op_sel_hi:[1,0]
	v_pk_mul_f32 v[56:57], v[56:57], v[138:139] op_sel_hi:[1,0]
	v_pk_mul_f32 v[58:59], v[58:59], v[138:139] op_sel_hi:[1,0]
	v_pk_mul_f32 v[52:53], v[52:53], v[138:139] op_sel_hi:[1,0]
	v_pk_mul_f32 v[54:55], v[54:55], v[138:139] op_sel_hi:[1,0]
	v_pk_mul_f32 v[48:49], v[48:49], v[138:139] op_sel_hi:[1,0]
	v_pk_mul_f32 v[50:51], v[50:51], v[138:139] op_sel_hi:[1,0]
	v_cvt_pk_bf16_f32 v146, v60, v61
	v_cvt_pk_bf16_f32 v147, v62, v63
	v_cvt_pk_bf16_f32 v148, v56, v57
	v_cvt_pk_bf16_f32 v149, v58, v59
	global_store_dwordx4 v130, v[146:149], s[6:7]
	v_cvt_pk_bf16_f32 v150, v52, v53
	v_cvt_pk_bf16_f32 v151, v54, v55
	v_cvt_pk_bf16_f32 v152, v48, v49
	v_cvt_pk_bf16_f32 v153, v50, v51
	global_store_dwordx4 v130, v[150:153], s[6:7] offset:256
	s_add_u32 s6, s6, s33
	s_addc_u32 s7, s7, 0
	v_pk_mul_f32 v[44:45], v[44:45], v[138:139] op_sel:[0,1] op_sel_hi:[1,1]
	v_pk_mul_f32 v[46:47], v[46:47], v[138:139] op_sel:[0,1] op_sel_hi:[1,1]
	v_pk_mul_f32 v[40:41], v[40:41], v[138:139] op_sel:[0,1] op_sel_hi:[1,1]
	v_pk_mul_f32 v[42:43], v[42:43], v[138:139] op_sel:[0,1] op_sel_hi:[1,1]
	v_pk_mul_f32 v[36:37], v[36:37], v[138:139] op_sel:[0,1] op_sel_hi:[1,1]
	v_pk_mul_f32 v[38:39], v[38:39], v[138:139] op_sel:[0,1] op_sel_hi:[1,1]
	v_pk_mul_f32 v[32:33], v[32:33], v[138:139] op_sel:[0,1] op_sel_hi:[1,1]
	v_pk_mul_f32 v[34:35], v[34:35], v[138:139] op_sel:[0,1] op_sel_hi:[1,1]
	v_cvt_pk_bf16_f32 v146, v44, v45
	v_cvt_pk_bf16_f32 v147, v46, v47
	v_cvt_pk_bf16_f32 v148, v40, v41
	v_cvt_pk_bf16_f32 v149, v42, v43
	global_store_dwordx4 v130, v[146:149], s[6:7]
	v_cvt_pk_bf16_f32 v150, v36, v37
	v_cvt_pk_bf16_f32 v151, v38, v39
	v_cvt_pk_bf16_f32 v152, v32, v33
	v_cvt_pk_bf16_f32 v153, v34, v35
	global_store_dwordx4 v130, v[150:153], s[6:7] offset:256
	s_add_u32 s6, s6, s33
	s_addc_u32 s7, s7, 0
	v_pk_mul_f32 v[28:29], v[28:29], v[140:141] op_sel_hi:[1,0]
	v_pk_mul_f32 v[30:31], v[30:31], v[140:141] op_sel_hi:[1,0]
	v_pk_mul_f32 v[24:25], v[24:25], v[140:141] op_sel_hi:[1,0]
	v_pk_mul_f32 v[26:27], v[26:27], v[140:141] op_sel_hi:[1,0]
	v_pk_mul_f32 v[20:21], v[20:21], v[140:141] op_sel_hi:[1,0]
	v_pk_mul_f32 v[22:23], v[22:23], v[140:141] op_sel_hi:[1,0]
	v_pk_mul_f32 v[16:17], v[16:17], v[140:141] op_sel_hi:[1,0]
	v_pk_mul_f32 v[18:19], v[18:19], v[140:141] op_sel_hi:[1,0]
	v_cvt_pk_bf16_f32 v146, v28, v29
	v_cvt_pk_bf16_f32 v147, v30, v31
	v_cvt_pk_bf16_f32 v148, v24, v25
	v_cvt_pk_bf16_f32 v149, v26, v27
	global_store_dwordx4 v130, v[146:149], s[6:7]
	v_cvt_pk_bf16_f32 v150, v20, v21
	v_cvt_pk_bf16_f32 v151, v22, v23
	v_cvt_pk_bf16_f32 v152, v16, v17
	v_cvt_pk_bf16_f32 v153, v18, v19
	global_store_dwordx4 v130, v[150:153], s[6:7] offset:256
	s_add_u32 s6, s6, s33
	s_addc_u32 s7, s7, 0
	v_pk_mul_f32 v[12:13], v[12:13], v[140:141] op_sel:[0,1] op_sel_hi:[1,1]
	v_pk_mul_f32 v[14:15], v[14:15], v[140:141] op_sel:[0,1] op_sel_hi:[1,1]
	v_pk_mul_f32 v[4:5], v[4:5], v[140:141] op_sel:[0,1] op_sel_hi:[1,1]
	v_pk_mul_f32 v[6:7], v[6:7], v[140:141] op_sel:[0,1] op_sel_hi:[1,1]
	v_pk_mul_f32 v[8:9], v[8:9], v[140:141] op_sel:[0,1] op_sel_hi:[1,1]
	v_pk_mul_f32 v[10:11], v[10:11], v[140:141] op_sel:[0,1] op_sel_hi:[1,1]
	v_pk_mul_f32 v[0:1], v[0:1], v[140:141] op_sel:[0,1] op_sel_hi:[1,1]
	v_pk_mul_f32 v[2:3], v[2:3], v[140:141] op_sel:[0,1] op_sel_hi:[1,1]
	v_cvt_pk_bf16_f32 v146, v12, v13
	v_cvt_pk_bf16_f32 v147, v14, v15
	v_cvt_pk_bf16_f32 v148, v4, v5
	v_cvt_pk_bf16_f32 v149, v6, v7
	global_store_dwordx4 v130, v[146:149], s[6:7]
	v_cvt_pk_bf16_f32 v150, v8, v9
	v_cvt_pk_bf16_f32 v151, v10, v11
	v_cvt_pk_bf16_f32 v152, v0, v1
	v_cvt_pk_bf16_f32 v153, v2, v3
	global_store_dwordx4 v130, v[150:153], s[6:7] offset:256
	s_branch .LBB0_971
